# fold -log2e into per-row rstd in P6 gate epilogue and both P8 ple-gate epilogues (drops the per-element pre-scale v_mul before v_exp)
# baseline (speedup 1.0000x reference)
.LBB0_1502:
	s_mov_b64 s[6:7], s[54:55]
	s_add_u32 s28, s6, 0x1a0d2000
	s_addc_u32 s29, s7, 0
	s_add_u32 s26, s6, 0x2580000
	s_addc_u32 s27, s7, 0
	s_add_u32 s22, s6, 0xa680000
	s_addc_u32 s23, s7, 0
	s_lshl_b32 s42, s20, 8
	s_lshl_b32 s43, s11, 6
	s_add_i32 s44, s43, s42
	v_or_b32_e32 v138, s44, v179
	v_mov_b32_e32 v175, v1
	v_lshl_add_u64 v[130:131], s[6:7], 0, v[174:175]
	s_mov_b64 s[6:7], 0xaa88000
	v_ashrrev_i32_e32 v139, 31, v138
	v_lshl_add_u64 v[140:141], v[130:131], 0, s[6:7]
	v_lshlrev_b64 v[130:131], 6, v[138:139]
	v_lshl_add_u64 v[146:147], v[140:141], 0, v[130:131]
	v_or_b32_e32 v130, 16, v138
	v_ashrrev_i32_e32 v131, 31, v130
	v_or_b32_e32 v142, 32, v138
	v_or_b32_e32 v138, 48, v138
	v_lshlrev_b64 v[130:131], 6, v[130:131]
	v_ashrrev_i32_e32 v143, 31, v142
	v_ashrrev_i32_e32 v139, 31, v138
	s_mov_b64 s[24:25], s[52:53]
	v_lshl_add_u64 v[134:135], v[140:141], 0, v[130:131]
	v_lshlrev_b64 v[142:143], 6, v[142:143]
	v_lshlrev_b64 v[138:139], 6, v[138:139]
	global_load_dwordx4 v[130:133], v[146:147], off
	s_nop 0
	global_load_dwordx4 v[134:137], v[134:135], off
	v_lshl_add_u64 v[142:143], v[140:141], 0, v[142:143]
	v_lshl_add_u64 v[144:145], v[140:141], 0, v[138:139]
	global_load_dwordx4 v[138:141], v[142:143], off
	s_nop 0
	global_load_dwordx4 v[142:145], v[144:145], off
	v_add_co_u32_e32 v158, vcc, s84, v146
	s_lshl_b32 s6, s18, 8
	s_nop 0
	v_addc_co_u32_e32 v159, vcc, 0, v147, vcc
	global_load_dwordx4 v[146:149], v[158:159], off
	global_load_dwordx4 v[150:153], v[158:159], off offset:1024
	global_load_dwordx4 v[154:157], v[158:159], off offset:2048
	global_load_dwordx4 v[162:165], v[158:159], off offset:3072
	s_lshl_b32 s7, s9, 5
	v_or_b32_e32 v158, s43, v179
	s_or_b32 s6, s7, s6
	v_add_u32_e32 v184, s42, v158
	v_lshl_or_b32 v176, v181, 3, s6
	v_ashrrev_i32_e32 v185, 31, v184
	v_ashrrev_i32_e32 v177, 31, v176
	v_lshlrev_b64 v[158:159], 10, v[184:185]
	v_lshl_add_u64 v[158:159], v[158:159], 0, v[176:177]
	v_lshlrev_b64 v[208:209], 1, v[158:159]
	v_lshl_add_u64 v[186:187], v[158:159], 2, s[24:25]
	v_lshl_add_u64 v[158:159], s[28:29], 0, v[208:209]
	global_load_dwordx4 v[166:169], v[186:187], off offset:16
	global_load_dwordx4 v[170:173], v[186:187], off
	global_load_dwordx4 v[190:193], v[158:159], off
	v_or_b32_e32 v208, 0x100, v208
	v_lshlrev_b64 v[212:213], 11, v[184:185]
	v_lshl_add_u64 v[212:213], s[26:27], 0, v[212:213]
	v_lshl_add_u64 v[212:213], v[176:177], 1, v[212:213]
	v_cmp_eq_u32_e32 vcc, 0, v181
	s_waitcnt vmcnt(0)
	v_mov_b32_e32 v158, v131
	v_mov_b32_e32 v159, v132
	v_mov_b32_e32 v131, v133
	v_pk_add_f32 v[130:131], v[158:159], v[130:131]
	v_add_f32_e32 v132, v134, v135
	v_add_f32_e32 v133, v136, v137
	v_add_f32_e32 v136, v142, v143
	v_add_f32_e32 v137, v144, v145
	v_add_f32_e32 v130, v130, v131
	v_add_f32_e32 v131, v132, v133
	v_add_f32_e32 v133, v136, v137
	ds_swizzle_b32 v136, v130 offset:swizzle(SWAP,16)
	ds_swizzle_b32 v137, v131 offset:swizzle(SWAP,16)
	v_add_f32_e32 v134, v138, v139
	v_add_f32_e32 v135, v140, v141
	v_add_f32_e32 v138, v146, v147
	s_waitcnt lgkmcnt(1)
	v_add_f32_e32 v130, v130, v136
	s_waitcnt lgkmcnt(0)
	v_add_f32_e32 v160, v131, v137
	v_mov_b32_e32 v131, v130
	s_nop 1
	v_permlane32_swap_b32_e32 v130, v131
	v_add_f32_e32 v130, v130, v131
	v_fmamk_f32 v130, v130, 0x3a800000, v254
	v_rsq_f32_e32 v188, v130
	s_nop 0
	v_mul_f32_e32 v188, 0xbfb8aa3b, v188
	v_add_f32_e32 v130, v154, v155
	v_add_f32_e32 v131, v156, v157
	v_add_f32_e32 v130, v130, v131
	v_add_f32_e32 v139, v148, v149
	v_add_f32_e32 v132, v134, v135
	ds_swizzle_b32 v131, v130 offset:swizzle(SWAP,16)
	v_add_f32_e32 v134, v138, v139
	ds_swizzle_b32 v138, v132 offset:swizzle(SWAP,16)
	ds_swizzle_b32 v139, v133 offset:swizzle(SWAP,16)
	v_add_f32_e32 v140, v150, v151
	s_waitcnt lgkmcnt(2)
	v_add_f32_e32 v198, v130, v131
	v_lshl_add_u64 v[130:131], s[28:29], 0, v[208:209]
	s_waitcnt lgkmcnt(1)
	v_add_f32_e32 v158, v132, v138
	s_waitcnt lgkmcnt(0)
	v_add_f32_e32 v195, v133, v139
	v_add_f32_e32 v132, v162, v163
	v_add_f32_e32 v133, v164, v165
	global_load_dwordx4 v[162:165], v[186:187], off offset:528
	global_load_dwordx4 v[204:207], v[186:187], off offset:512
	global_load_dwordx4 v[208:211], v[130:131], off
	v_add_f32_e32 v141, v152, v153
	v_add_f32_e32 v135, v140, v141
	ds_swizzle_b32 v140, v134 offset:swizzle(SWAP,16)
	ds_swizzle_b32 v141, v135 offset:swizzle(SWAP,16)
	v_add_f32_e32 v132, v132, v133
	v_or_b32_e32 v154, 16, v184
	ds_swizzle_b32 v133, v132 offset:swizzle(SWAP,16)
	v_ashrrev_i32_e32 v155, 31, v154
	v_lshlrev_b64 v[156:157], 10, v[154:155]
	v_lshl_add_u64 v[130:131], v[156:157], 0, v[176:177]
	v_lshlrev_b64 v[136:137], 1, v[130:131]
	s_waitcnt lgkmcnt(2)
	v_add_f32_e32 v189, v134, v140
	s_waitcnt lgkmcnt(1)
	v_add_f32_e32 v200, v135, v141
	v_lshl_add_u64 v[134:135], v[130:131], 2, s[24:25]
	v_lshl_add_u64 v[146:147], s[28:29], 0, v[136:137]
	v_or_b32_e32 v136, 0x100, v136
	s_waitcnt lgkmcnt(0)
	v_add_f32_e32 v175, v132, v133
	global_load_dwordx4 v[142:145], v[134:135], off offset:16
	global_load_dwordx4 v[150:153], v[134:135], off
	global_load_dwordx4 v[130:133], v[134:135], off offset:528
	global_load_dwordx4 v[138:141], v[134:135], off offset:512
	v_lshl_add_u64 v[134:135], s[28:29], 0, v[136:137]
	global_load_dwordx4 v[146:149], v[146:147], off
	s_nop 0
	global_load_dwordx4 v[134:137], v[134:135], off
	v_mov_b32_e32 v194, v189
	s_nop 1
	v_permlane32_swap_b32_e32 v189, v194
	v_pk_mul_f32 v[216:217], v[126:127], v[188:189] op_sel_hi:[1,0]
	v_pk_mul_f32 v[214:215], v[128:129], v[188:189] op_sel_hi:[1,0]
	v_exp_f32_e32 v203, v216
	v_exp_f32_e32 v221, v217
	v_lshlrev_b32_e32 v222, 16, v190
	v_add_f32_e32 v203, 1.0, v203
	v_rcp_f32_e32 v220, v203
	v_add_f32_e32 v203, 1.0, v221
	v_and_b32_e32 v223, 0xffff0000, v190
	v_rcp_f32_e32 v221, v203
	v_exp_f32_e32 v190, v214
	v_exp_f32_e32 v203, v215
	v_pk_mul_f32 v[216:217], v[122:123], v[188:189] op_sel_hi:[1,0]
	v_add_f32_e32 v190, 1.0, v190
	v_rcp_f32_e32 v214, v190
	v_add_f32_e32 v190, 1.0, v203
	v_rcp_f32_e32 v215, v190
	v_exp_f32_e32 v203, v216
	v_pk_mul_f32 v[218:219], v[124:125], v[188:189] op_sel_hi:[1,0]
	v_lshlrev_b32_e32 v190, 16, v191
	v_and_b32_e32 v191, 0xffff0000, v191
	v_pk_fma_f32 v[172:173], v[214:215], v[190:191], v[172:173]
	v_add_f32_e32 v190, 1.0, v203
	v_exp_f32_e32 v216, v217
	v_exp_f32_e32 v203, v218
	v_exp_f32_e32 v217, v219
	v_add_f32_e32 v191, 1.0, v216
	v_lshlrev_b32_e32 v214, 16, v192
	v_and_b32_e32 v215, 0xffff0000, v192
	v_add_f32_e32 v192, 1.0, v203
	v_rcp_f32_e32 v190, v190
	v_rcp_f32_e32 v191, v191
	v_rcp_f32_e32 v216, v192
	v_add_f32_e32 v192, 1.0, v217
	v_rcp_f32_e32 v217, v192
	v_lshlrev_b64 v[186:187], 12, v[184:185]
	v_lshl_add_u64 v[186:187], s[24:25], 0, v[186:187]
	v_pk_fma_f32 v[166:167], v[190:191], v[214:215], v[166:167]
	v_lshlrev_b32_e32 v190, 16, v193
	v_and_b32_e32 v191, 0xffff0000, v193
	v_pk_fma_f32 v[170:171], v[220:221], v[222:223], v[170:171]
	v_pk_fma_f32 v[168:169], v[216:217], v[190:191], v[168:169]
	v_lshl_add_u64 v[186:187], v[176:177], 2, v[186:187]
	global_store_dwordx4 v[186:187], v[170:173], off
	global_store_dwordx4 v[186:187], v[166:169], off offset:16
	v_pk_mul_f32 v[190:191], v[170:171], v[170:171]
	v_pk_mul_f32 v[192:193], v[172:173], v[172:173]
	v_pk_mul_f32 v[216:217], v[168:169], v[168:169]
	v_cvt_pk_bf16_f32 v170, v170, v171
	v_cvt_pk_bf16_f32 v171, v172, v173
	v_cvt_pk_bf16_f32 v173, v168, v169
	v_pk_mul_f32 v[168:169], v[118:119], v[188:189] op_sel_hi:[1,0]
	v_cvt_pk_bf16_f32 v172, v166, v167
	global_store_dwordx4 v[212:213], v[170:173], off
	v_pk_mul_f32 v[214:215], v[166:167], v[166:167]
	v_pk_mul_f32 v[166:167], v[120:121], v[188:189] op_sel_hi:[1,0]
	v_exp_f32_e32 v172, v168
	v_exp_f32_e32 v173, v169
	v_pk_mul_f32 v[170:171], v[116:117], v[188:189] op_sel_hi:[1,0]
	v_pk_mul_f32 v[168:169], v[114:115], v[188:189] op_sel_hi:[1,0]
	v_add_f32_e32 v172, 1.0, v172
	v_add_f32_e32 v173, 1.0, v173
	v_exp_f32_e32 v188, v166
	v_rcp_f32_e32 v172, v172
	v_rcp_f32_e32 v173, v173
	v_exp_f32_e32 v203, v167
	s_waitcnt vmcnt(9)
	v_lshlrev_b32_e32 v218, 16, v208
	v_and_b32_e32 v219, 0xffff0000, v208
	v_pk_fma_f32 v[166:167], v[172:173], v[218:219], v[204:205]
	v_add_f32_e32 v172, 1.0, v188
	v_add_f32_e32 v173, 1.0, v203
	v_exp_f32_e32 v188, v168
	v_rcp_f32_e32 v172, v172
	v_rcp_f32_e32 v173, v173
	v_exp_f32_e32 v203, v169
	v_exp_f32_e32 v170, v170
	v_exp_f32_e32 v171, v171
	v_lshlrev_b32_e32 v204, 16, v209
	v_and_b32_e32 v205, 0xffff0000, v209
	v_pk_fma_f32 v[168:169], v[172:173], v[204:205], v[206:207]
	v_add_f32_e32 v172, 1.0, v188
	v_add_f32_e32 v173, 1.0, v203
	v_rcp_f32_e32 v172, v172
	v_rcp_f32_e32 v173, v173
	v_add_f32_e32 v170, 1.0, v170
	v_add_f32_e32 v171, 1.0, v171
	v_rcp_f32_e32 v170, v170
	v_rcp_f32_e32 v171, v171
	v_lshlrev_b32_e32 v204, 16, v210
	v_and_b32_e32 v205, 0xffff0000, v210
	v_pk_fma_f32 v[162:163], v[172:173], v[204:205], v[162:163]
	v_lshlrev_b32_e32 v172, 16, v211
	v_and_b32_e32 v173, 0xffff0000, v211
	v_pk_fma_f32 v[164:165], v[170:171], v[172:173], v[164:165]
	v_pk_mul_f32 v[170:171], v[166:167], v[166:167]
	v_pk_mul_f32 v[172:173], v[168:169], v[168:169]
	v_add_f32_e32 v170, v170, v171
	v_add_f32_e32 v172, v172, v173
	global_store_dwordx4 v[186:187], v[166:169], off offset:512
	global_store_dwordx4 v[186:187], v[162:165], off offset:528
	v_pk_mul_f32 v[186:187], v[162:163], v[162:163]
	v_pk_mul_f32 v[204:205], v[164:165], v[164:165]
	v_add_f32_e32 v170, v170, v172
	v_add_f32_e32 v171, v216, v217
	v_add_f32_e32 v172, v214, v215
	v_add_f32_e32 v188, v204, v205
	v_add_f32_e32 v186, v186, v187
	v_add_f32_e32 v171, v172, v171
	v_add_f32_e32 v172, v192, v193
	v_add_f32_e32 v173, v190, v191
	v_add_f32_e32 v186, v186, v188
	v_add_f32_e32 v172, v173, v172
	v_add_f32_e32 v170, v170, v186
	v_add_f32_e32 v171, v172, v171
	v_add_f32_e32 v170, v171, v170
	ds_swizzle_b32 v171, v170 offset:swizzle(SWAP,16)
	v_cvt_pk_bf16_f32 v166, v166, v167
	v_cvt_pk_bf16_f32 v167, v168, v169
	v_cvt_pk_bf16_f32 v168, v162, v163
	v_mov_b32_e32 v161, v160
	s_waitcnt lgkmcnt(0)
	v_add_f32_e32 v162, v170, v171
	v_mov_b32_e32 v159, v158
	v_mov_b32_e32 v202, v195
	v_mov_b32_e32 v201, v200
	v_mov_b32_e32 v199, v198
	v_mov_b32_e32 v183, v175
	v_mov_b32_e32 v163, v162
	v_permlane32_swap_b32_e32 v160, v161
	v_permlane32_swap_b32_e32 v158, v159
	v_permlane32_swap_b32_e32 v195, v202
	v_permlane32_swap_b32_e32 v200, v201
	v_permlane32_swap_b32_e32 v198, v199
	v_permlane32_swap_b32_e32 v175, v183
	v_cvt_pk_bf16_f32 v169, v164, v165
	v_permlane32_swap_b32_e32 v162, v163
	global_store_dwordx4 v[212:213], v[166:169], off offset:256
	s_and_saveexec_b64 s[6:7], vcc
	s_cbranch_execz .LBB0_1504
	v_add_f32_e32 v164, v162, v163
	v_lshlrev_b64 v[162:163], 6, v[184:185]
	s_lshl_b32 s42, s18, 2
	v_lshl_add_u64 v[162:163], s[22:23], 0, v[162:163]
	s_ashr_i32 s43, s42, 31
	v_lshl_add_u64 v[162:163], s[42:43], 2, v[162:163]
	s_lshl_b32 s68, s9, 2
	v_lshl_add_u64 v[162:163], v[162:163], 0, s[68:69]
	global_store_dword v[162:163], v164, off
.LBB0_1504:
	s_or_b64 exec, exec, s[6:7]
	v_add_f32_e32 v160, v160, v161
	v_fmamk_f32 v160, v160, 0x3a800000, v254
	v_rsq_f32_e32 v160, v160
	s_nop 0
	v_mul_f32_e32 v160, 0xbfb8aa3b, v160
	s_waitcnt vmcnt(7)
	v_lshlrev_b32_e32 v172, 16, v146
	v_and_b32_e32 v173, 0xffff0000, v146
	v_lshl_add_u64 v[162:163], v[156:157], 2, s[24:25]
	v_pk_mul_f32 v[166:167], v[110:111], v[160:161] op_sel_hi:[1,0]
	v_pk_mul_f32 v[164:165], v[112:113], v[160:161] op_sel_hi:[1,0]
	v_pk_mul_f32 v[168:169], v[108:109], v[160:161] op_sel_hi:[1,0]
	v_exp_f32_e32 v161, v166
	v_exp_f32_e32 v171, v167
	v_pk_mul_f32 v[166:167], v[106:107], v[160:161] op_sel_hi:[1,0]
	v_add_f32_e32 v161, 1.0, v161
	v_rcp_f32_e32 v170, v161
	v_add_f32_e32 v161, 1.0, v171
	v_rcp_f32_e32 v171, v161
	v_exp_f32_e32 v146, v164
	v_exp_f32_e32 v161, v165
	v_pk_fma_f32 v[150:151], v[170:171], v[172:173], v[150:151]
	v_add_f32_e32 v146, 1.0, v146
	v_rcp_f32_e32 v164, v146
	v_add_f32_e32 v146, 1.0, v161
	v_rcp_f32_e32 v165, v146
	v_exp_f32_e32 v161, v166
	v_lshlrev_b32_e32 v146, 16, v147
	v_and_b32_e32 v147, 0xffff0000, v147
	v_pk_fma_f32 v[152:153], v[164:165], v[146:147], v[152:153]
	v_add_f32_e32 v146, 1.0, v161
	v_exp_f32_e32 v166, v167
	v_exp_f32_e32 v161, v168
	v_exp_f32_e32 v167, v169
	v_add_f32_e32 v147, 1.0, v166
	v_lshlrev_b32_e32 v164, 16, v148
	v_and_b32_e32 v165, 0xffff0000, v148
	v_add_f32_e32 v148, 1.0, v161
	v_rcp_f32_e32 v146, v146
	v_rcp_f32_e32 v147, v147
	v_rcp_f32_e32 v166, v148
	v_add_f32_e32 v148, 1.0, v167
	v_rcp_f32_e32 v167, v148
	v_pk_fma_f32 v[142:143], v[146:147], v[164:165], v[142:143]
	v_lshlrev_b32_e32 v146, 16, v149
	v_and_b32_e32 v147, 0xffff0000, v149
	v_pk_fma_f32 v[144:145], v[166:167], v[146:147], v[144:145]
	v_lshl_add_u64 v[162:163], v[176:177], 2, v[162:163]
	global_store_dwordx4 v[162:163], v[150:153], off
	global_store_dwordx4 v[162:163], v[142:145], off offset:16
	v_pk_mul_f32 v[170:171], v[144:145], v[144:145]
	v_cvt_pk_bf16_f32 v149, v144, v145
	v_pk_mul_f32 v[144:145], v[104:105], v[160:161] op_sel_hi:[1,0]
	v_pk_mul_f32 v[166:167], v[152:153], v[152:153]
	v_cvt_pk_bf16_f32 v147, v152, v153
	s_waitcnt vmcnt(8)
	v_lshlrev_b32_e32 v152, 16, v134
	v_and_b32_e32 v153, 0xffff0000, v134
	v_lshl_add_u64 v[156:157], v[156:157], 1, s[26:27]
	v_exp_f32_e32 v134, v144
	v_pk_mul_f32 v[168:169], v[142:143], v[142:143]
	v_cvt_pk_bf16_f32 v146, v150, v151
	v_cvt_pk_bf16_f32 v148, v142, v143
	v_lshl_add_u64 v[142:143], v[176:177], 1, v[156:157]
	v_exp_f32_e32 v145, v145
	global_store_dwordx4 v[142:143], v[146:149], off
	v_pk_mul_f32 v[164:165], v[150:151], v[150:151]
	v_add_f32_e32 v134, 1.0, v134
	v_pk_mul_f32 v[146:147], v[102:103], v[160:161] op_sel_hi:[1,0]
	v_rcp_f32_e32 v144, v134
	v_exp_f32_e32 v150, v146
	v_exp_f32_e32 v151, v147
	v_pk_mul_f32 v[146:147], v[98:99], v[160:161] op_sel_hi:[1,0]
	v_add_f32_e32 v134, 1.0, v145
	v_rcp_f32_e32 v145, v134
	v_exp_f32_e32 v146, v146
	v_exp_f32_e32 v147, v147
	v_pk_mul_f32 v[148:149], v[100:101], v[160:161] op_sel_hi:[1,0]
	v_lshlrev_b32_e32 v134, 16, v135
	v_and_b32_e32 v135, 0xffff0000, v135
	v_pk_fma_f32 v[140:141], v[144:145], v[134:135], v[140:141]
	v_add_f32_e32 v134, 1.0, v146
	v_exp_f32_e32 v146, v148
	v_add_f32_e32 v135, 1.0, v147
	v_exp_f32_e32 v147, v149
	v_add_f32_e32 v150, 1.0, v150
	v_add_f32_e32 v151, 1.0, v151
	v_lshlrev_b32_e32 v144, 16, v136
	v_and_b32_e32 v145, 0xffff0000, v136
	v_add_f32_e32 v136, 1.0, v146
	v_rcp_f32_e32 v150, v150
	v_rcp_f32_e32 v151, v151
	v_rcp_f32_e32 v134, v134
	v_rcp_f32_e32 v135, v135
	v_rcp_f32_e32 v146, v136
	v_add_f32_e32 v136, 1.0, v147
	v_rcp_f32_e32 v147, v136
	v_pk_fma_f32 v[138:139], v[150:151], v[152:153], v[138:139]
	v_pk_fma_f32 v[130:131], v[134:135], v[144:145], v[130:131]
	v_lshlrev_b32_e32 v134, 16, v137
	v_and_b32_e32 v135, 0xffff0000, v137
	v_pk_fma_f32 v[132:133], v[146:147], v[134:135], v[132:133]
	v_pk_mul_f32 v[134:135], v[138:139], v[138:139]
	v_pk_mul_f32 v[136:137], v[140:141], v[140:141]
	v_add_f32_e32 v134, v134, v135
	v_add_f32_e32 v136, v136, v137
	v_pk_mul_f32 v[144:145], v[130:131], v[130:131]
	v_pk_mul_f32 v[146:147], v[132:133], v[132:133]
	v_add_f32_e32 v134, v134, v136
	v_add_f32_e32 v135, v170, v171
	v_add_f32_e32 v136, v168, v169
	v_add_f32_e32 v146, v146, v147
	v_add_f32_e32 v144, v144, v145
	v_add_f32_e32 v135, v136, v135
	v_add_f32_e32 v136, v166, v167
	v_add_f32_e32 v137, v164, v165
	v_add_f32_e32 v144, v144, v146
	v_add_f32_e32 v136, v137, v136
	v_add_f32_e32 v134, v134, v144
	v_add_f32_e32 v135, v136, v135
	v_add_f32_e32 v144, v135, v134
	global_store_dwordx4 v[162:163], v[138:141], off offset:512
	global_store_dwordx4 v[162:163], v[130:133], off offset:528
	v_cvt_pk_bf16_f32 v134, v138, v139
	ds_swizzle_b32 v138, v144 offset:swizzle(SWAP,16)
	v_cvt_pk_bf16_f32 v136, v130, v131
	v_cvt_pk_bf16_f32 v135, v140, v141
	v_cvt_pk_bf16_f32 v137, v132, v133
	global_store_dwordx4 v[142:143], v[134:137], off offset:256
	s_waitcnt lgkmcnt(0)
	v_add_f32_e32 v130, v144, v138
	v_mov_b32_e32 v131, v130
	s_nop 1
	v_permlane32_swap_b32_e32 v130, v131
	s_and_saveexec_b64 s[6:7], vcc
	s_cbranch_execz .LBB0_1506
	v_add_f32_e32 v132, v130, v131
	v_lshlrev_b64 v[130:131], 6, v[154:155]
	s_lshl_b32 s42, s18, 2
	v_lshl_add_u64 v[130:131], s[22:23], 0, v[130:131]
	s_ashr_i32 s43, s42, 31
	v_lshl_add_u64 v[130:131], s[42:43], 2, v[130:131]
	s_lshl_b32 s68, s9, 2
	v_lshl_add_u64 v[130:131], v[130:131], 0, s[68:69]
	global_store_dword v[130:131], v132, off
.LBB0_1506:
	s_or_b64 exec, exec, s[6:7]
	v_add_f32_e32 v130, v158, v159
	v_add_u32_e32 v186, 32, v184
	v_fmamk_f32 v130, v130, 0x3a800000, v254
	v_ashrrev_i32_e32 v187, 31, v186
	v_rsq_f32_e32 v188, v130
	s_nop 0
	v_mul_f32_e32 v188, 0xbfb8aa3b, v188
	v_lshlrev_b64 v[130:131], 10, v[186:187]
	v_lshl_add_u64 v[130:131], v[130:131], 0, v[176:177]
	v_lshl_add_u64 v[132:133], v[130:131], 2, s[24:25]
	v_lshlrev_b64 v[130:131], 1, v[130:131]
	global_load_dwordx4 v[170:173], v[132:133], off offset:16
	global_load_dwordx4 v[166:169], v[132:133], off
	v_lshl_add_u64 v[134:135], s[28:29], 0, v[130:131]
	global_load_dwordx4 v[204:207], v[134:135], off
	global_load_dwordx4 v[154:157], v[132:133], off offset:528
	global_load_dwordx4 v[162:165], v[132:133], off offset:512
	v_or_b32_e32 v130, 0x100, v130
	v_lshl_add_u64 v[130:131], s[28:29], 0, v[130:131]
	global_load_dwordx4 v[158:161], v[130:131], off
	v_pk_mul_f32 v[210:211], v[94:95], v[188:189] op_sel_hi:[1,0]
	v_pk_mul_f32 v[208:209], v[96:97], v[188:189] op_sel_hi:[1,0]
	v_exp_f32_e32 v185, v210
	v_add_u32_e32 v130, 48, v184
	v_ashrrev_i32_e32 v131, 31, v130
	v_lshlrev_b64 v[130:131], 10, v[130:131]
	v_add_f32_e32 v185, 1.0, v185
	v_rcp_f32_e32 v210, v185
	v_exp_f32_e32 v185, v211
	v_lshl_add_u64 v[130:131], v[130:131], 0, v[176:177]
	v_lshlrev_b64 v[136:137], 1, v[130:131]
	v_pk_mul_f32 v[214:215], v[90:91], v[188:189] op_sel_hi:[1,0]
	v_add_f32_e32 v185, 1.0, v185
	v_rcp_f32_e32 v211, v185
	v_exp_f32_e32 v185, v208
	v_lshl_add_u64 v[134:135], v[130:131], 2, s[24:25]
	v_lshl_add_u64 v[130:131], s[28:29], 0, v[136:137]
	v_or_b32_e32 v136, 0x100, v136
	v_add_f32_e32 v185, 1.0, v185
	v_rcp_f32_e32 v208, v185
	v_exp_f32_e32 v185, v209
	global_load_dwordx4 v[142:145], v[134:135], off offset:16
	global_load_dwordx4 v[150:153], v[134:135], off
	global_load_dwordx4 v[146:149], v[130:131], off
	s_nop 0
	global_load_dwordx4 v[130:133], v[134:135], off offset:528
	global_load_dwordx4 v[138:141], v[134:135], off offset:512
	v_lshl_add_u64 v[134:135], s[28:29], 0, v[136:137]
	v_add_f32_e32 v185, 1.0, v185
	v_rcp_f32_e32 v209, v185
	v_exp_f32_e32 v185, v214
	global_load_dwordx4 v[134:137], v[134:135], off
	v_pk_mul_f32 v[212:213], v[92:93], v[188:189] op_sel_hi:[1,0]
	v_lshlrev_b64 v[190:191], 12, v[186:187]
	v_add_f32_e32 v185, 1.0, v185
	v_lshl_add_u64 v[192:193], s[24:25], 0, v[190:191]
	v_lshlrev_b64 v[190:191], 11, v[186:187]
	v_lshl_add_u64 v[190:191], s[26:27], 0, v[190:191]
	v_lshl_add_u64 v[192:193], v[176:177], 2, v[192:193]
	s_waitcnt vmcnt(9)
	v_lshlrev_b32_e32 v216, 16, v204
	v_and_b32_e32 v217, 0xffff0000, v204
	v_lshlrev_b32_e32 v204, 16, v205
	v_and_b32_e32 v205, 0xffff0000, v205
	v_pk_fma_f32 v[168:169], v[208:209], v[204:205], v[168:169]
	v_rcp_f32_e32 v204, v185
	v_exp_f32_e32 v185, v215
	v_lshlrev_b32_e32 v208, 16, v206
	v_and_b32_e32 v209, 0xffff0000, v206
	v_lshlrev_b32_e32 v206, 16, v207
	v_add_f32_e32 v185, 1.0, v185
	v_rcp_f32_e32 v205, v185
	v_exp_f32_e32 v185, v212
	v_and_b32_e32 v207, 0xffff0000, v207
	v_pk_fma_f32 v[170:171], v[204:205], v[208:209], v[170:171]
	v_pk_fma_f32 v[166:167], v[210:211], v[216:217], v[166:167]
	v_add_f32_e32 v185, 1.0, v185
	v_rcp_f32_e32 v204, v185
	v_exp_f32_e32 v185, v213
	v_pk_mul_f32 v[208:209], v[170:171], v[170:171]
	s_waitcnt vmcnt(6)
	v_lshlrev_b32_e32 v212, 16, v158
	v_and_b32_e32 v213, 0xffff0000, v158
	v_add_f32_e32 v185, 1.0, v185
	v_rcp_f32_e32 v205, v185
	s_nop 0
	v_pk_fma_f32 v[172:173], v[204:205], v[206:207], v[172:173]
	global_store_dwordx4 v[192:193], v[166:169], off
	global_store_dwordx4 v[192:193], v[170:173], off offset:16
	v_pk_mul_f32 v[204:205], v[166:167], v[166:167]
	v_pk_mul_f32 v[206:207], v[168:169], v[168:169]
	v_cvt_pk_bf16_f32 v166, v166, v167
	v_cvt_pk_bf16_f32 v167, v168, v169
	v_cvt_pk_bf16_f32 v168, v170, v171
	v_cvt_pk_bf16_f32 v169, v172, v173
	v_lshl_add_u64 v[170:171], v[176:177], 1, v[190:191]
	global_store_dwordx4 v[170:171], v[166:169], off
	v_pk_mul_f32 v[190:191], v[82:83], v[188:189] op_sel_hi:[1,0]
	v_pk_mul_f32 v[210:211], v[172:173], v[172:173]
	v_pk_mul_f32 v[166:167], v[88:89], v[188:189] op_sel_hi:[1,0]
	v_pk_mul_f32 v[168:169], v[86:87], v[188:189] op_sel_hi:[1,0]
	v_exp_f32_e32 v158, v166
	v_pk_mul_f32 v[172:173], v[84:85], v[188:189] op_sel_hi:[1,0]
	v_add_f32_e32 v158, 1.0, v158
	v_rcp_f32_e32 v166, v158
	v_exp_f32_e32 v158, v167
	v_exp_f32_e32 v168, v168
	v_exp_f32_e32 v169, v169
	v_add_f32_e32 v158, 1.0, v158
	v_rcp_f32_e32 v167, v158
	v_lshlrev_b32_e32 v158, 16, v159
	v_and_b32_e32 v159, 0xffff0000, v159
	v_add_f32_e32 v168, 1.0, v168
	v_pk_fma_f32 v[164:165], v[166:167], v[158:159], v[164:165]
	v_exp_f32_e32 v158, v190
	v_exp_f32_e32 v159, v191
	v_lshlrev_b32_e32 v166, 16, v160
	v_and_b32_e32 v167, 0xffff0000, v160
	v_add_f32_e32 v158, 1.0, v158
	v_add_f32_e32 v159, 1.0, v159
	v_rcp_f32_e32 v158, v158
	v_rcp_f32_e32 v159, v159
	v_add_f32_e32 v169, 1.0, v169
	v_rcp_f32_e32 v168, v168
	v_rcp_f32_e32 v169, v169
	v_pk_fma_f32 v[154:155], v[158:159], v[166:167], v[154:155]
	v_exp_f32_e32 v158, v172
	v_exp_f32_e32 v159, v173
	v_pk_fma_f32 v[162:163], v[168:169], v[212:213], v[162:163]
	v_lshlrev_b32_e32 v160, 16, v161
	v_add_f32_e32 v158, 1.0, v158
	v_add_f32_e32 v159, 1.0, v159
	v_rcp_f32_e32 v158, v158
	v_rcp_f32_e32 v159, v159
	v_and_b32_e32 v161, 0xffff0000, v161
	v_pk_mul_f32 v[166:167], v[154:155], v[154:155]
	v_pk_fma_f32 v[156:157], v[158:159], v[160:161], v[156:157]
	v_pk_mul_f32 v[158:159], v[162:163], v[162:163]
	v_pk_mul_f32 v[160:161], v[164:165], v[164:165]
	v_add_f32_e32 v158, v158, v159
	v_add_f32_e32 v160, v160, v161
	v_pk_mul_f32 v[168:169], v[156:157], v[156:157]
	v_add_f32_e32 v158, v158, v160
	v_add_f32_e32 v159, v210, v211
	v_add_f32_e32 v160, v208, v209
	v_add_f32_e32 v168, v168, v169
	v_add_f32_e32 v166, v166, v167
	v_add_f32_e32 v159, v160, v159
	v_add_f32_e32 v160, v206, v207
	v_add_f32_e32 v161, v204, v205
	v_add_f32_e32 v166, v166, v168
	v_add_f32_e32 v160, v161, v160
	v_add_f32_e32 v158, v158, v166
	v_add_f32_e32 v159, v160, v159
	v_add_f32_e32 v166, v159, v158
	global_store_dwordx4 v[192:193], v[162:165], off offset:512
	global_store_dwordx4 v[192:193], v[154:157], off offset:528
	v_cvt_pk_bf16_f32 v160, v154, v155
	ds_swizzle_b32 v154, v166 offset:swizzle(SWAP,16)
	v_cvt_pk_bf16_f32 v158, v162, v163
	v_cvt_pk_bf16_f32 v159, v164, v165
	v_cvt_pk_bf16_f32 v161, v156, v157
	global_store_dwordx4 v[170:171], v[158:161], off offset:256
	s_waitcnt lgkmcnt(0)
	v_add_f32_e32 v154, v166, v154
	v_mov_b32_e32 v155, v154
	s_nop 1
	v_permlane32_swap_b32_e32 v154, v155
	s_and_saveexec_b64 s[6:7], vcc
	s_cbranch_execz .LBB0_1508
	v_add_f32_e32 v156, v154, v155
	v_lshlrev_b64 v[154:155], 6, v[186:187]
	s_lshl_b32 s42, s18, 2
	v_lshl_add_u64 v[154:155], s[22:23], 0, v[154:155]
	s_ashr_i32 s43, s42, 31
	v_lshl_add_u64 v[154:155], s[42:43], 2, v[154:155]
	s_lshl_b32 s68, s9, 2
	v_lshl_add_u64 v[154:155], v[154:155], 0, s[68:69]
	global_store_dword v[154:155], v156, off
.LBB0_1508:
	s_or_b64 exec, exec, s[6:7]
	v_add_f32_e32 v154, v195, v202
	v_fmamk_f32 v154, v154, 0x3a800000, v254
	v_rsq_f32_e32 v156, v154
	s_nop 0
	v_mul_f32_e32 v156, 0xbfb8aa3b, v156
	s_waitcnt vmcnt(9)
	v_lshlrev_b32_e32 v170, 16, v146
	v_and_b32_e32 v171, 0xffff0000, v146
	v_or_b32_e32 v154, 48, v184
	v_pk_mul_f32 v[164:165], v[78:79], v[156:157] op_sel_hi:[1,0]
	v_pk_mul_f32 v[162:163], v[80:81], v[156:157] op_sel_hi:[1,0]
	v_pk_mul_f32 v[166:167], v[76:77], v[156:157] op_sel_hi:[1,0]
	v_exp_f32_e32 v157, v164
	v_exp_f32_e32 v169, v165
	v_pk_mul_f32 v[164:165], v[74:75], v[156:157] op_sel_hi:[1,0]
	v_add_f32_e32 v157, 1.0, v157
	v_rcp_f32_e32 v168, v157
	v_add_f32_e32 v157, 1.0, v169
	v_rcp_f32_e32 v169, v157
	v_exp_f32_e32 v146, v162
	v_exp_f32_e32 v157, v163
	v_ashrrev_i32_e32 v155, 31, v154
	v_add_f32_e32 v146, 1.0, v146
	v_rcp_f32_e32 v162, v146
	v_add_f32_e32 v146, 1.0, v157
	v_rcp_f32_e32 v163, v146
	v_exp_f32_e32 v157, v164
	v_lshlrev_b32_e32 v146, 16, v147
	v_and_b32_e32 v147, 0xffff0000, v147
	v_pk_fma_f32 v[152:153], v[162:163], v[146:147], v[152:153]
	v_add_f32_e32 v146, 1.0, v157
	v_exp_f32_e32 v164, v165
	v_exp_f32_e32 v157, v166
	v_exp_f32_e32 v165, v167
	v_add_f32_e32 v147, 1.0, v164
	v_lshlrev_b32_e32 v162, 16, v148
	v_and_b32_e32 v163, 0xffff0000, v148
	v_add_f32_e32 v148, 1.0, v157
	v_rcp_f32_e32 v146, v146
	v_rcp_f32_e32 v147, v147
	v_rcp_f32_e32 v164, v148
	v_add_f32_e32 v148, 1.0, v165
	v_rcp_f32_e32 v165, v148
	v_lshlrev_b64 v[158:159], 12, v[154:155]
	v_lshl_add_u64 v[158:159], s[24:25], 0, v[158:159]
	v_pk_fma_f32 v[142:143], v[146:147], v[162:163], v[142:143]
	v_lshlrev_b32_e32 v146, 16, v149
	v_and_b32_e32 v147, 0xffff0000, v149
	v_pk_fma_f32 v[150:151], v[168:169], v[170:171], v[150:151]
	v_pk_fma_f32 v[144:145], v[164:165], v[146:147], v[144:145]
	v_lshl_add_u64 v[158:159], v[176:177], 2, v[158:159]
	global_store_dwordx4 v[158:159], v[150:153], off
	global_store_dwordx4 v[158:159], v[142:145], off offset:16
	v_pk_mul_f32 v[168:169], v[144:145], v[144:145]
	v_cvt_pk_bf16_f32 v149, v144, v145
	v_pk_mul_f32 v[144:145], v[72:73], v[156:157] op_sel_hi:[1,0]
	v_lshlrev_b64 v[160:161], 11, v[154:155]
	v_pk_mul_f32 v[164:165], v[152:153], v[152:153]
	v_cvt_pk_bf16_f32 v147, v152, v153
	s_waitcnt vmcnt(8)
	v_lshlrev_b32_e32 v152, 16, v134
	v_and_b32_e32 v153, 0xffff0000, v134
	v_lshl_add_u64 v[160:161], s[26:27], 0, v[160:161]
	v_exp_f32_e32 v134, v144
	v_pk_mul_f32 v[166:167], v[142:143], v[142:143]
	v_cvt_pk_bf16_f32 v146, v150, v151
	v_cvt_pk_bf16_f32 v148, v142, v143
	v_lshl_add_u64 v[142:143], v[176:177], 1, v[160:161]
	v_exp_f32_e32 v145, v145
	global_store_dwordx4 v[142:143], v[146:149], off
	v_pk_mul_f32 v[162:163], v[150:151], v[150:151]
	v_add_f32_e32 v134, 1.0, v134
	v_pk_mul_f32 v[146:147], v[70:71], v[156:157] op_sel_hi:[1,0]
	v_rcp_f32_e32 v144, v134
	v_exp_f32_e32 v150, v146
	v_exp_f32_e32 v151, v147
	v_pk_mul_f32 v[146:147], v[66:67], v[156:157] op_sel_hi:[1,0]
	v_add_f32_e32 v134, 1.0, v145
	v_rcp_f32_e32 v145, v134
	v_exp_f32_e32 v146, v146
	v_exp_f32_e32 v147, v147
	v_pk_mul_f32 v[148:149], v[68:69], v[156:157] op_sel_hi:[1,0]
	v_lshlrev_b32_e32 v134, 16, v135
	v_and_b32_e32 v135, 0xffff0000, v135
	v_pk_fma_f32 v[140:141], v[144:145], v[134:135], v[140:141]
	v_add_f32_e32 v134, 1.0, v146
	v_exp_f32_e32 v146, v148
	v_add_f32_e32 v135, 1.0, v147
	v_exp_f32_e32 v147, v149
	v_add_f32_e32 v150, 1.0, v150
	v_add_f32_e32 v151, 1.0, v151
	v_lshlrev_b32_e32 v144, 16, v136
	v_and_b32_e32 v145, 0xffff0000, v136
	v_add_f32_e32 v136, 1.0, v146
	v_rcp_f32_e32 v150, v150
	v_rcp_f32_e32 v151, v151
	v_rcp_f32_e32 v134, v134
	v_rcp_f32_e32 v135, v135
	v_rcp_f32_e32 v146, v136
	v_add_f32_e32 v136, 1.0, v147
	v_rcp_f32_e32 v147, v136
	v_pk_fma_f32 v[138:139], v[150:151], v[152:153], v[138:139]
	v_pk_fma_f32 v[130:131], v[134:135], v[144:145], v[130:131]
	v_lshlrev_b32_e32 v134, 16, v137
	v_and_b32_e32 v135, 0xffff0000, v137
	v_pk_fma_f32 v[132:133], v[146:147], v[134:135], v[132:133]
	v_pk_mul_f32 v[134:135], v[138:139], v[138:139]
	v_pk_mul_f32 v[136:137], v[140:141], v[140:141]
	v_add_f32_e32 v134, v134, v135
	v_add_f32_e32 v136, v136, v137
	v_pk_mul_f32 v[144:145], v[130:131], v[130:131]
	v_pk_mul_f32 v[146:147], v[132:133], v[132:133]
	v_add_f32_e32 v134, v134, v136
	v_add_f32_e32 v135, v168, v169
	v_add_f32_e32 v136, v166, v167
	v_add_f32_e32 v146, v146, v147
	v_add_f32_e32 v144, v144, v145
	v_add_f32_e32 v135, v136, v135
	v_add_f32_e32 v136, v164, v165
	v_add_f32_e32 v137, v162, v163
	v_add_f32_e32 v144, v144, v146
	v_add_f32_e32 v136, v137, v136
	v_add_f32_e32 v134, v134, v144
	v_add_f32_e32 v135, v136, v135
	v_add_f32_e32 v144, v135, v134
	global_store_dwordx4 v[158:159], v[138:141], off offset:512
	global_store_dwordx4 v[158:159], v[130:133], off offset:528
	v_cvt_pk_bf16_f32 v134, v138, v139
	ds_swizzle_b32 v138, v144 offset:swizzle(SWAP,16)
	v_cvt_pk_bf16_f32 v136, v130, v131
	v_cvt_pk_bf16_f32 v135, v140, v141
	v_cvt_pk_bf16_f32 v137, v132, v133
	global_store_dwordx4 v[142:143], v[134:137], off offset:256
	s_waitcnt lgkmcnt(0)
	v_add_f32_e32 v130, v144, v138
	v_mov_b32_e32 v131, v130
	s_nop 1
	v_permlane32_swap_b32_e32 v130, v131
	s_and_saveexec_b64 s[6:7], vcc
	s_cbranch_execz .LBB0_1510
	v_add_f32_e32 v132, v130, v131
	v_lshlrev_b64 v[130:131], 6, v[154:155]
	s_lshl_b32 s42, s18, 2
	v_lshl_add_u64 v[130:131], s[22:23], 0, v[130:131]
	s_ashr_i32 s43, s42, 31
	v_lshl_add_u64 v[130:131], s[42:43], 2, v[130:131]
	s_lshl_b32 s68, s9, 2
	v_lshl_add_u64 v[130:131], v[130:131], 0, s[68:69]
	global_store_dword v[130:131], v132, off
.LBB0_1510:
	s_or_b64 exec, exec, s[6:7]
	v_add_f32_e32 v130, v189, v194
	v_add_u32_e32 v188, 0x80, v184
	v_fmamk_f32 v130, v130, 0x3a800000, v254
	v_ashrrev_i32_e32 v189, 31, v188
	v_rsq_f32_e32 v190, v130
	s_nop 0
	v_mul_f32_e32 v190, 0xbfb8aa3b, v190
	v_lshlrev_b64 v[130:131], 10, v[188:189]
	v_lshl_add_u64 v[130:131], v[130:131], 0, v[176:177]
	v_lshl_add_u64 v[132:133], v[130:131], 2, s[24:25]
	v_lshlrev_b64 v[130:131], 1, v[130:131]
	global_load_dwordx4 v[170:173], v[132:133], off offset:16
	global_load_dwordx4 v[166:169], v[132:133], off
	v_lshl_add_u64 v[134:135], s[28:29], 0, v[130:131]
	global_load_dwordx4 v[202:205], v[134:135], off
	global_load_dwordx4 v[154:157], v[132:133], off offset:528
	global_load_dwordx4 v[162:165], v[132:133], off offset:512
	v_or_b32_e32 v130, 0x100, v130
	v_lshl_add_u64 v[130:131], s[28:29], 0, v[130:131]
	global_load_dwordx4 v[158:161], v[130:131], off
	v_pk_mul_f32 v[208:209], v[62:63], v[190:191] op_sel_hi:[1,0]
	v_pk_mul_f32 v[206:207], v[64:65], v[190:191] op_sel_hi:[1,0]
	v_exp_f32_e32 v185, v208
	v_add_u32_e32 v186, 0x90, v184
	v_ashrrev_i32_e32 v187, 31, v186
	v_lshlrev_b64 v[130:131], 10, v[186:187]
	v_add_f32_e32 v185, 1.0, v185
	v_rcp_f32_e32 v208, v185
	v_exp_f32_e32 v185, v209
	v_lshl_add_u64 v[130:131], v[130:131], 0, v[176:177]
	v_lshlrev_b64 v[136:137], 1, v[130:131]
	v_pk_mul_f32 v[212:213], v[58:59], v[190:191] op_sel_hi:[1,0]
	v_add_f32_e32 v185, 1.0, v185
	v_rcp_f32_e32 v209, v185
	v_exp_f32_e32 v185, v206
	v_lshl_add_u64 v[134:135], v[130:131], 2, s[24:25]
	v_lshl_add_u64 v[130:131], s[28:29], 0, v[136:137]
	v_or_b32_e32 v136, 0x100, v136
	v_add_f32_e32 v185, 1.0, v185
	v_rcp_f32_e32 v206, v185
	v_exp_f32_e32 v185, v207
	global_load_dwordx4 v[142:145], v[134:135], off offset:16
	global_load_dwordx4 v[150:153], v[134:135], off
	global_load_dwordx4 v[146:149], v[130:131], off
	s_nop 0
	global_load_dwordx4 v[130:133], v[134:135], off offset:528
	global_load_dwordx4 v[138:141], v[134:135], off offset:512
	v_lshl_add_u64 v[134:135], s[28:29], 0, v[136:137]
	v_add_f32_e32 v185, 1.0, v185
	v_rcp_f32_e32 v207, v185
	v_exp_f32_e32 v185, v212
	global_load_dwordx4 v[134:137], v[134:135], off
	v_pk_mul_f32 v[210:211], v[60:61], v[190:191] op_sel_hi:[1,0]
	v_lshlrev_b64 v[192:193], 12, v[188:189]
	v_add_f32_e32 v185, 1.0, v185
	v_lshl_add_u64 v[194:195], s[24:25], 0, v[192:193]
	v_lshlrev_b64 v[192:193], 11, v[188:189]
	v_lshl_add_u64 v[192:193], s[26:27], 0, v[192:193]
	v_lshl_add_u64 v[194:195], v[176:177], 2, v[194:195]
	s_waitcnt vmcnt(9)
	v_lshlrev_b32_e32 v214, 16, v202
	v_and_b32_e32 v215, 0xffff0000, v202
	v_lshlrev_b32_e32 v202, 16, v203
	v_and_b32_e32 v203, 0xffff0000, v203
	v_pk_fma_f32 v[168:169], v[206:207], v[202:203], v[168:169]
	v_rcp_f32_e32 v202, v185
	v_exp_f32_e32 v185, v213
	v_lshlrev_b32_e32 v206, 16, v204
	v_and_b32_e32 v207, 0xffff0000, v204
	v_lshlrev_b32_e32 v204, 16, v205
	v_add_f32_e32 v185, 1.0, v185
	v_rcp_f32_e32 v203, v185
	v_exp_f32_e32 v185, v210
	v_and_b32_e32 v205, 0xffff0000, v205
	v_pk_fma_f32 v[170:171], v[202:203], v[206:207], v[170:171]
	v_pk_fma_f32 v[166:167], v[208:209], v[214:215], v[166:167]
	v_add_f32_e32 v185, 1.0, v185
	v_rcp_f32_e32 v202, v185
	v_exp_f32_e32 v185, v211
	v_pk_mul_f32 v[206:207], v[170:171], v[170:171]
	v_add_f32_e32 v185, 1.0, v185
	v_rcp_f32_e32 v203, v185
	s_nop 0
	v_pk_fma_f32 v[172:173], v[202:203], v[204:205], v[172:173]
	global_store_dwordx4 v[194:195], v[166:169], off
	global_store_dwordx4 v[194:195], v[170:173], off offset:16
	v_pk_mul_f32 v[202:203], v[166:167], v[166:167]
	v_pk_mul_f32 v[204:205], v[168:169], v[168:169]
	v_cvt_pk_bf16_f32 v166, v166, v167
	v_cvt_pk_bf16_f32 v167, v168, v169
	v_cvt_pk_bf16_f32 v168, v170, v171
	v_cvt_pk_bf16_f32 v169, v172, v173
	v_lshl_add_u64 v[170:171], v[176:177], 1, v[192:193]
	global_store_dwordx4 v[170:171], v[166:169], off
	s_waitcnt vmcnt(9)
	v_lshlrev_b32_e32 v192, 16, v158
	v_and_b32_e32 v193, 0xffff0000, v158
	v_pk_mul_f32 v[166:167], v[56:57], v[190:191] op_sel_hi:[1,0]
	v_pk_mul_f32 v[208:209], v[172:173], v[172:173]
	v_exp_f32_e32 v158, v166
	v_pk_mul_f32 v[168:169], v[54:55], v[190:191] op_sel_hi:[1,0]
	v_pk_mul_f32 v[172:173], v[52:53], v[190:191] op_sel_hi:[1,0]
	v_pk_mul_f32 v[190:191], v[50:51], v[190:191] op_sel_hi:[1,0]
	v_add_f32_e32 v158, 1.0, v158
	v_rcp_f32_e32 v166, v158
	v_exp_f32_e32 v158, v167
	v_exp_f32_e32 v168, v168
	v_add_f32_e32 v158, 1.0, v158
	v_rcp_f32_e32 v167, v158
	v_lshlrev_b32_e32 v158, 16, v159
	v_and_b32_e32 v159, 0xffff0000, v159
	v_exp_f32_e32 v169, v169
	v_pk_fma_f32 v[164:165], v[166:167], v[158:159], v[164:165]
	v_exp_f32_e32 v158, v190
	v_exp_f32_e32 v159, v191
	v_lshlrev_b32_e32 v166, 16, v160
	v_and_b32_e32 v167, 0xffff0000, v160
	v_add_f32_e32 v158, 1.0, v158
	v_add_f32_e32 v159, 1.0, v159
	v_rcp_f32_e32 v158, v158
	v_rcp_f32_e32 v159, v159
	v_add_f32_e32 v168, 1.0, v168
	v_add_f32_e32 v169, 1.0, v169
	v_rcp_f32_e32 v168, v168
	v_pk_fma_f32 v[154:155], v[158:159], v[166:167], v[154:155]
	v_exp_f32_e32 v158, v172
	v_exp_f32_e32 v159, v173
	v_rcp_f32_e32 v169, v169
	v_lshlrev_b32_e32 v160, 16, v161
	v_add_f32_e32 v158, 1.0, v158
	v_add_f32_e32 v159, 1.0, v159
	v_rcp_f32_e32 v158, v158
	v_rcp_f32_e32 v159, v159
	v_pk_fma_f32 v[162:163], v[168:169], v[192:193], v[162:163]
	v_and_b32_e32 v161, 0xffff0000, v161
	v_pk_mul_f32 v[166:167], v[154:155], v[154:155]
	v_pk_fma_f32 v[156:157], v[158:159], v[160:161], v[156:157]
	v_pk_mul_f32 v[158:159], v[162:163], v[162:163]
	v_pk_mul_f32 v[160:161], v[164:165], v[164:165]
	v_add_f32_e32 v158, v158, v159
	v_add_f32_e32 v160, v160, v161
	v_pk_mul_f32 v[168:169], v[156:157], v[156:157]
	v_add_f32_e32 v158, v158, v160
	v_add_f32_e32 v159, v208, v209
	v_add_f32_e32 v160, v206, v207
	v_add_f32_e32 v168, v168, v169
	v_add_f32_e32 v166, v166, v167
	v_add_f32_e32 v159, v160, v159
	v_add_f32_e32 v160, v204, v205
	v_add_f32_e32 v161, v202, v203
	v_add_f32_e32 v166, v166, v168
	v_add_f32_e32 v160, v161, v160
	v_add_f32_e32 v158, v158, v166
	v_add_f32_e32 v159, v160, v159
	v_add_f32_e32 v166, v159, v158
	global_store_dwordx4 v[194:195], v[162:165], off offset:512
	global_store_dwordx4 v[194:195], v[154:157], off offset:528
	v_cvt_pk_bf16_f32 v160, v154, v155
	ds_swizzle_b32 v154, v166 offset:swizzle(SWAP,16)
	v_cvt_pk_bf16_f32 v158, v162, v163
	v_cvt_pk_bf16_f32 v159, v164, v165
	v_cvt_pk_bf16_f32 v161, v156, v157
	global_store_dwordx4 v[170:171], v[158:161], off offset:256
	s_waitcnt lgkmcnt(0)
	v_add_f32_e32 v154, v166, v154
	v_mov_b32_e32 v155, v154
	s_nop 1
	v_permlane32_swap_b32_e32 v154, v155
	s_and_saveexec_b64 s[6:7], vcc
	s_cbranch_execz .LBB0_1512
	v_add_f32_e32 v156, v154, v155
	v_lshlrev_b64 v[154:155], 6, v[188:189]
	s_lshl_b32 s42, s18, 2
	v_lshl_add_u64 v[154:155], s[22:23], 0, v[154:155]
	s_ashr_i32 s43, s42, 31
	v_lshl_add_u64 v[154:155], s[42:43], 2, v[154:155]
	s_lshl_b32 s68, s9, 2
	v_lshl_add_u64 v[154:155], v[154:155], 0, s[68:69]
	global_store_dword v[154:155], v156, off
.LBB0_1512:
	s_or_b64 exec, exec, s[6:7]
	v_add_f32_e32 v154, v200, v201
	v_fmamk_f32 v154, v154, 0x3a800000, v254
	v_rsq_f32_e32 v154, v154
	s_nop 0
	v_mul_f32_e32 v154, 0xbfb8aa3b, v154
	s_waitcnt vmcnt(9)
	v_lshlrev_b32_e32 v168, 16, v146
	v_and_b32_e32 v169, 0xffff0000, v146
	v_lshlrev_b64 v[156:157], 12, v[186:187]
	v_pk_mul_f32 v[162:163], v[46:47], v[154:155] op_sel_hi:[1,0]
	v_pk_mul_f32 v[160:161], v[48:49], v[154:155] op_sel_hi:[1,0]
	v_pk_mul_f32 v[164:165], v[44:45], v[154:155] op_sel_hi:[1,0]
	v_exp_f32_e32 v155, v162
	v_exp_f32_e32 v167, v163
	v_pk_mul_f32 v[162:163], v[42:43], v[154:155] op_sel_hi:[1,0]
	v_add_f32_e32 v155, 1.0, v155
	v_rcp_f32_e32 v166, v155
	v_add_f32_e32 v155, 1.0, v167
	v_rcp_f32_e32 v167, v155
	v_exp_f32_e32 v146, v160
	v_exp_f32_e32 v155, v161
	v_lshl_add_u64 v[156:157], s[24:25], 0, v[156:157]
	v_add_f32_e32 v146, 1.0, v146
	v_rcp_f32_e32 v160, v146
	v_add_f32_e32 v146, 1.0, v155
	v_rcp_f32_e32 v161, v146
	v_exp_f32_e32 v155, v162
	v_lshlrev_b32_e32 v146, 16, v147
	v_and_b32_e32 v147, 0xffff0000, v147
	v_pk_fma_f32 v[152:153], v[160:161], v[146:147], v[152:153]
	v_add_f32_e32 v146, 1.0, v155
	v_exp_f32_e32 v162, v163
	v_exp_f32_e32 v155, v164
	v_exp_f32_e32 v163, v165
	v_add_f32_e32 v147, 1.0, v162
	v_lshlrev_b32_e32 v160, 16, v148
	v_and_b32_e32 v161, 0xffff0000, v148
	v_add_f32_e32 v148, 1.0, v155
	v_rcp_f32_e32 v146, v146
	v_rcp_f32_e32 v147, v147
	v_rcp_f32_e32 v162, v148
	v_add_f32_e32 v148, 1.0, v163
	v_rcp_f32_e32 v163, v148
	v_pk_fma_f32 v[142:143], v[146:147], v[160:161], v[142:143]
	v_lshlrev_b32_e32 v146, 16, v149
	v_and_b32_e32 v147, 0xffff0000, v149
	v_pk_fma_f32 v[150:151], v[166:167], v[168:169], v[150:151]
	v_pk_fma_f32 v[144:145], v[162:163], v[146:147], v[144:145]
	v_lshl_add_u64 v[156:157], v[176:177], 2, v[156:157]
	global_store_dwordx4 v[156:157], v[150:153], off
	global_store_dwordx4 v[156:157], v[142:145], off offset:16
	v_pk_mul_f32 v[166:167], v[144:145], v[144:145]
	v_cvt_pk_bf16_f32 v149, v144, v145
	v_pk_mul_f32 v[144:145], v[40:41], v[154:155] op_sel_hi:[1,0]
	v_lshlrev_b64 v[158:159], 11, v[186:187]
	v_pk_mul_f32 v[162:163], v[152:153], v[152:153]
	v_cvt_pk_bf16_f32 v147, v152, v153
	s_waitcnt vmcnt(8)
	v_lshlrev_b32_e32 v152, 16, v134
	v_and_b32_e32 v153, 0xffff0000, v134
	v_lshl_add_u64 v[158:159], s[26:27], 0, v[158:159]
	v_exp_f32_e32 v134, v144
	v_pk_mul_f32 v[164:165], v[142:143], v[142:143]
	v_cvt_pk_bf16_f32 v146, v150, v151
	v_cvt_pk_bf16_f32 v148, v142, v143
	v_lshl_add_u64 v[142:143], v[176:177], 1, v[158:159]
	v_exp_f32_e32 v145, v145
	global_store_dwordx4 v[142:143], v[146:149], off
	v_pk_mul_f32 v[160:161], v[150:151], v[150:151]
	v_add_f32_e32 v134, 1.0, v134
	v_pk_mul_f32 v[146:147], v[38:39], v[154:155] op_sel_hi:[1,0]
	v_rcp_f32_e32 v144, v134
	v_exp_f32_e32 v150, v146
	v_exp_f32_e32 v151, v147
	v_pk_mul_f32 v[146:147], v[34:35], v[154:155] op_sel_hi:[1,0]
	v_add_f32_e32 v134, 1.0, v145
	v_rcp_f32_e32 v145, v134
	v_exp_f32_e32 v146, v146
	v_exp_f32_e32 v147, v147
	v_pk_mul_f32 v[148:149], v[36:37], v[154:155] op_sel_hi:[1,0]
	v_lshlrev_b32_e32 v134, 16, v135
	v_and_b32_e32 v135, 0xffff0000, v135
	v_pk_fma_f32 v[140:141], v[144:145], v[134:135], v[140:141]
	v_add_f32_e32 v134, 1.0, v146
	v_exp_f32_e32 v146, v148
	v_add_f32_e32 v135, 1.0, v147
	v_exp_f32_e32 v147, v149
	v_add_f32_e32 v150, 1.0, v150
	v_add_f32_e32 v151, 1.0, v151
	v_lshlrev_b32_e32 v144, 16, v136
	v_and_b32_e32 v145, 0xffff0000, v136
	v_add_f32_e32 v136, 1.0, v146
	v_rcp_f32_e32 v150, v150
	v_rcp_f32_e32 v151, v151
	v_rcp_f32_e32 v134, v134
	v_rcp_f32_e32 v135, v135
	v_rcp_f32_e32 v146, v136
	v_add_f32_e32 v136, 1.0, v147
	v_rcp_f32_e32 v147, v136
	v_pk_fma_f32 v[138:139], v[150:151], v[152:153], v[138:139]
	v_pk_fma_f32 v[130:131], v[134:135], v[144:145], v[130:131]
	v_lshlrev_b32_e32 v134, 16, v137
	v_and_b32_e32 v135, 0xffff0000, v137
	v_pk_fma_f32 v[132:133], v[146:147], v[134:135], v[132:133]
	v_pk_mul_f32 v[134:135], v[138:139], v[138:139]
	v_pk_mul_f32 v[136:137], v[140:141], v[140:141]
	v_add_f32_e32 v134, v134, v135
	v_add_f32_e32 v136, v136, v137
	v_pk_mul_f32 v[144:145], v[130:131], v[130:131]
	v_pk_mul_f32 v[146:147], v[132:133], v[132:133]
	v_add_f32_e32 v134, v134, v136
	v_add_f32_e32 v135, v166, v167
	v_add_f32_e32 v136, v164, v165
	v_add_f32_e32 v146, v146, v147
	v_add_f32_e32 v144, v144, v145
	v_add_f32_e32 v135, v136, v135
	v_add_f32_e32 v136, v162, v163
	v_add_f32_e32 v137, v160, v161
	v_add_f32_e32 v144, v144, v146
	v_add_f32_e32 v136, v137, v136
	v_add_f32_e32 v134, v134, v144
	v_add_f32_e32 v135, v136, v135
	v_add_f32_e32 v144, v135, v134
	global_store_dwordx4 v[156:157], v[138:141], off offset:512
	global_store_dwordx4 v[156:157], v[130:133], off offset:528
	v_cvt_pk_bf16_f32 v134, v138, v139
	ds_swizzle_b32 v138, v144 offset:swizzle(SWAP,16)
	v_cvt_pk_bf16_f32 v136, v130, v131
	v_cvt_pk_bf16_f32 v135, v140, v141
	v_cvt_pk_bf16_f32 v137, v132, v133
	global_store_dwordx4 v[142:143], v[134:137], off offset:256
	s_waitcnt lgkmcnt(0)
	v_add_f32_e32 v130, v144, v138
	v_mov_b32_e32 v131, v130
	s_nop 1
	v_permlane32_swap_b32_e32 v130, v131
	s_and_saveexec_b64 s[6:7], vcc
	s_cbranch_execz .LBB0_1514
	v_add_f32_e32 v132, v130, v131
	v_lshlrev_b64 v[130:131], 6, v[186:187]
	s_lshl_b32 s42, s18, 2
	v_lshl_add_u64 v[130:131], s[22:23], 0, v[130:131]
	s_ashr_i32 s43, s42, 31
	v_lshl_add_u64 v[130:131], s[42:43], 2, v[130:131]
	s_lshl_b32 s68, s9, 2
	v_lshl_add_u64 v[130:131], v[130:131], 0, s[68:69]
	global_store_dword v[130:131], v132, off
.LBB0_1514:
	s_or_b64 exec, exec, s[6:7]
	v_add_f32_e32 v130, v198, v199
	v_add_u32_e32 v186, 0xa0, v184
	v_fmamk_f32 v130, v130, 0x3a800000, v254
	v_ashrrev_i32_e32 v187, 31, v186
	v_rsq_f32_e32 v188, v130
	s_nop 0
	v_mul_f32_e32 v188, 0xbfb8aa3b, v188
	v_lshlrev_b64 v[130:131], 10, v[186:187]
	v_lshl_add_u64 v[130:131], v[130:131], 0, v[176:177]
	v_lshl_add_u64 v[132:133], v[130:131], 2, s[24:25]
	v_lshlrev_b64 v[130:131], 1, v[130:131]
	global_load_dwordx4 v[170:173], v[132:133], off offset:16
	global_load_dwordx4 v[166:169], v[132:133], off
	v_lshl_add_u64 v[134:135], s[28:29], 0, v[130:131]
	global_load_dwordx4 v[198:201], v[134:135], off
	global_load_dwordx4 v[154:157], v[132:133], off offset:528
	global_load_dwordx4 v[162:165], v[132:133], off offset:512
	v_or_b32_e32 v130, 0x100, v130
	v_lshl_add_u64 v[130:131], s[28:29], 0, v[130:131]
	global_load_dwordx4 v[158:161], v[130:131], off
	v_pk_mul_f32 v[202:203], v[30:31], v[188:189] op_sel_hi:[1,0]
	v_pk_mul_f32 v[194:195], v[32:33], v[188:189] op_sel_hi:[1,0]
	v_pk_mul_f32 v[204:205], v[28:29], v[188:189] op_sel_hi:[1,0]
	v_pk_mul_f32 v[206:207], v[26:27], v[188:189] op_sel_hi:[1,0]
	v_exp_f32_e32 v189, v202
	v_add_u32_e32 v184, 0xb0, v184
	v_ashrrev_i32_e32 v185, 31, v184
	v_lshlrev_b64 v[130:131], 10, v[184:185]
	v_add_f32_e32 v189, 1.0, v189
	v_rcp_f32_e32 v202, v189
	v_exp_f32_e32 v189, v203
	v_lshl_add_u64 v[130:131], v[130:131], 0, v[176:177]
	v_lshlrev_b64 v[136:137], 1, v[130:131]
	v_lshl_add_u64 v[134:135], v[130:131], 2, s[24:25]
	v_add_f32_e32 v189, 1.0, v189
	v_rcp_f32_e32 v203, v189
	v_exp_f32_e32 v189, v194
	v_lshl_add_u64 v[130:131], s[28:29], 0, v[136:137]
	v_or_b32_e32 v136, 0x100, v136
	global_load_dwordx4 v[142:145], v[134:135], off offset:16
	global_load_dwordx4 v[150:153], v[134:135], off
	v_add_f32_e32 v189, 1.0, v189
	v_rcp_f32_e32 v194, v189
	v_exp_f32_e32 v189, v195
	global_load_dwordx4 v[146:149], v[130:131], off
	s_nop 0
	global_load_dwordx4 v[130:133], v[134:135], off offset:528
	global_load_dwordx4 v[138:141], v[134:135], off offset:512
	v_lshl_add_u64 v[134:135], s[28:29], 0, v[136:137]
	global_load_dwordx4 v[134:137], v[134:135], off
	v_add_f32_e32 v189, 1.0, v189
	v_rcp_f32_e32 v195, v189
	v_exp_f32_e32 v189, v206
	v_lshlrev_b64 v[190:191], 12, v[186:187]
	v_lshl_add_u64 v[192:193], s[24:25], 0, v[190:191]
	v_lshlrev_b64 v[190:191], 11, v[186:187]
	v_add_f32_e32 v189, 1.0, v189
	v_lshl_add_u64 v[190:191], s[26:27], 0, v[190:191]
	v_lshl_add_u64 v[192:193], v[176:177], 2, v[192:193]
	s_waitcnt vmcnt(9)
	v_lshlrev_b32_e32 v208, 16, v198
	v_and_b32_e32 v209, 0xffff0000, v198
	v_lshlrev_b32_e32 v198, 16, v199
	v_and_b32_e32 v199, 0xffff0000, v199
	v_pk_fma_f32 v[168:169], v[194:195], v[198:199], v[168:169]
	v_rcp_f32_e32 v194, v189
	v_exp_f32_e32 v189, v207
	v_lshlrev_b32_e32 v198, 16, v200
	v_and_b32_e32 v199, 0xffff0000, v200
	v_pk_fma_f32 v[166:167], v[202:203], v[208:209], v[166:167]
	v_add_f32_e32 v189, 1.0, v189
	v_rcp_f32_e32 v195, v189
	v_exp_f32_e32 v189, v204
	v_pk_fma_f32 v[170:171], v[194:195], v[198:199], v[170:171]
	v_lshlrev_b32_e32 v198, 16, v201
	v_add_f32_e32 v189, 1.0, v189
	v_rcp_f32_e32 v194, v189
	v_exp_f32_e32 v189, v205
	v_and_b32_e32 v199, 0xffff0000, v201
	v_pk_mul_f32 v[200:201], v[170:171], v[170:171]
	v_add_f32_e32 v189, 1.0, v189
	v_rcp_f32_e32 v195, v189
	s_nop 0
	v_pk_fma_f32 v[172:173], v[194:195], v[198:199], v[172:173]
	global_store_dwordx4 v[192:193], v[166:169], off
	global_store_dwordx4 v[192:193], v[170:173], off offset:16
	v_pk_mul_f32 v[194:195], v[166:167], v[166:167]
	v_pk_mul_f32 v[198:199], v[168:169], v[168:169]
	v_cvt_pk_bf16_f32 v166, v166, v167
	v_cvt_pk_bf16_f32 v167, v168, v169
	v_cvt_pk_bf16_f32 v168, v170, v171
	v_cvt_pk_bf16_f32 v169, v172, v173
	v_lshl_add_u64 v[170:171], v[176:177], 1, v[190:191]
	global_store_dwordx4 v[170:171], v[166:169], off
	s_waitcnt vmcnt(9)
	v_lshlrev_b32_e32 v190, 16, v158
	v_and_b32_e32 v191, 0xffff0000, v158
	v_pk_mul_f32 v[166:167], v[24:25], v[188:189] op_sel_hi:[1,0]
	v_pk_mul_f32 v[202:203], v[172:173], v[172:173]
	v_exp_f32_e32 v158, v166
	v_pk_mul_f32 v[168:169], v[22:23], v[188:189] op_sel_hi:[1,0]
	v_pk_mul_f32 v[172:173], v[20:21], v[188:189] op_sel_hi:[1,0]
	v_pk_mul_f32 v[188:189], v[18:19], v[188:189] op_sel_hi:[1,0]
	v_add_f32_e32 v158, 1.0, v158
	v_rcp_f32_e32 v166, v158
	v_exp_f32_e32 v158, v167
	v_exp_f32_e32 v168, v168
	v_add_f32_e32 v158, 1.0, v158
	v_rcp_f32_e32 v167, v158
	v_lshlrev_b32_e32 v158, 16, v159
	v_and_b32_e32 v159, 0xffff0000, v159
	v_exp_f32_e32 v169, v169
	v_pk_fma_f32 v[164:165], v[166:167], v[158:159], v[164:165]
	v_exp_f32_e32 v158, v188
	v_exp_f32_e32 v159, v189
	v_lshlrev_b32_e32 v166, 16, v160
	v_and_b32_e32 v167, 0xffff0000, v160
	v_add_f32_e32 v158, 1.0, v158
	v_add_f32_e32 v159, 1.0, v159
	v_rcp_f32_e32 v158, v158
	v_rcp_f32_e32 v159, v159
	v_add_f32_e32 v168, 1.0, v168
	v_add_f32_e32 v169, 1.0, v169
	v_rcp_f32_e32 v168, v168
	v_pk_fma_f32 v[154:155], v[158:159], v[166:167], v[154:155]
	v_exp_f32_e32 v158, v172
	v_exp_f32_e32 v159, v173
	v_rcp_f32_e32 v169, v169
	v_lshlrev_b32_e32 v160, 16, v161
	v_add_f32_e32 v158, 1.0, v158
	v_add_f32_e32 v159, 1.0, v159
	v_rcp_f32_e32 v158, v158
	v_rcp_f32_e32 v159, v159
	v_pk_fma_f32 v[162:163], v[168:169], v[190:191], v[162:163]
	v_and_b32_e32 v161, 0xffff0000, v161
	v_pk_mul_f32 v[166:167], v[154:155], v[154:155]
	v_pk_fma_f32 v[156:157], v[158:159], v[160:161], v[156:157]
	v_pk_mul_f32 v[158:159], v[162:163], v[162:163]
	v_pk_mul_f32 v[160:161], v[164:165], v[164:165]
	v_add_f32_e32 v158, v158, v159
	v_add_f32_e32 v160, v160, v161
	v_pk_mul_f32 v[168:169], v[156:157], v[156:157]
	v_add_f32_e32 v158, v158, v160
	v_add_f32_e32 v159, v202, v203
	v_add_f32_e32 v160, v200, v201
	v_add_f32_e32 v168, v168, v169
	v_add_f32_e32 v166, v166, v167
	v_add_f32_e32 v159, v160, v159
	v_add_f32_e32 v160, v198, v199
	v_add_f32_e32 v161, v194, v195
	v_add_f32_e32 v166, v166, v168
	v_add_f32_e32 v160, v161, v160
	v_add_f32_e32 v158, v158, v166
	v_add_f32_e32 v159, v160, v159
	v_add_f32_e32 v166, v159, v158
	global_store_dwordx4 v[192:193], v[162:165], off offset:512
	global_store_dwordx4 v[192:193], v[154:157], off offset:528
	v_cvt_pk_bf16_f32 v160, v154, v155
	ds_swizzle_b32 v154, v166 offset:swizzle(SWAP,16)
	v_cvt_pk_bf16_f32 v158, v162, v163
	v_cvt_pk_bf16_f32 v159, v164, v165
	v_cvt_pk_bf16_f32 v161, v156, v157
	global_store_dwordx4 v[170:171], v[158:161], off offset:256
	s_waitcnt lgkmcnt(0)
	v_add_f32_e32 v154, v166, v154
	v_mov_b32_e32 v155, v154
	s_nop 1
	v_permlane32_swap_b32_e32 v154, v155
	s_and_saveexec_b64 s[6:7], vcc
	s_cbranch_execz .LBB0_1516
	v_add_f32_e32 v156, v154, v155
	v_lshlrev_b64 v[154:155], 6, v[186:187]
	s_lshl_b32 s28, s18, 2
	v_lshl_add_u64 v[154:155], s[22:23], 0, v[154:155]
	s_ashr_i32 s29, s28, 31
	v_lshl_add_u64 v[154:155], s[28:29], 2, v[154:155]
	s_lshl_b32 s68, s9, 2
	v_lshl_add_u64 v[154:155], v[154:155], 0, s[68:69]
	global_store_dword v[154:155], v156, off
.LBB0_1516:
	s_or_b64 exec, exec, s[6:7]
	v_add_f32_e32 v154, v175, v183
	v_fmamk_f32 v154, v154, 0x3a800000, v254
	v_rsq_f32_e32 v154, v154
	s_nop 0
	v_mul_f32_e32 v154, 0xbfb8aa3b, v154
	s_waitcnt vmcnt(9)
	v_lshlrev_b32_e32 v168, 16, v146
	v_and_b32_e32 v169, 0xffff0000, v146
	v_lshlrev_b64 v[156:157], 12, v[184:185]
	v_pk_mul_f32 v[162:163], v[14:15], v[154:155] op_sel_hi:[1,0]
	v_pk_mul_f32 v[160:161], v[16:17], v[154:155] op_sel_hi:[1,0]
	v_pk_mul_f32 v[164:165], v[12:13], v[154:155] op_sel_hi:[1,0]
	v_exp_f32_e32 v155, v162
	v_exp_f32_e32 v167, v163
	v_pk_mul_f32 v[162:163], v[10:11], v[154:155] op_sel_hi:[1,0]
	v_add_f32_e32 v155, 1.0, v155
	v_rcp_f32_e32 v166, v155
	v_add_f32_e32 v155, 1.0, v167
	v_rcp_f32_e32 v167, v155
	v_exp_f32_e32 v146, v160
	v_exp_f32_e32 v155, v161
	v_lshl_add_u64 v[156:157], s[24:25], 0, v[156:157]
	v_add_f32_e32 v146, 1.0, v146
	v_rcp_f32_e32 v160, v146
	v_add_f32_e32 v146, 1.0, v155
	v_rcp_f32_e32 v161, v146
	v_exp_f32_e32 v155, v162
	v_lshlrev_b32_e32 v146, 16, v147
	v_and_b32_e32 v147, 0xffff0000, v147
	v_pk_fma_f32 v[152:153], v[160:161], v[146:147], v[152:153]
	v_add_f32_e32 v146, 1.0, v155
	v_exp_f32_e32 v162, v163
	v_exp_f32_e32 v155, v164
	v_exp_f32_e32 v163, v165
	v_add_f32_e32 v147, 1.0, v162
	v_lshlrev_b32_e32 v160, 16, v148
	v_and_b32_e32 v161, 0xffff0000, v148
	v_add_f32_e32 v148, 1.0, v155
	v_rcp_f32_e32 v146, v146
	v_rcp_f32_e32 v147, v147
	v_rcp_f32_e32 v162, v148
	v_add_f32_e32 v148, 1.0, v163
	v_rcp_f32_e32 v163, v148
	v_pk_fma_f32 v[142:143], v[146:147], v[160:161], v[142:143]
	v_lshlrev_b32_e32 v146, 16, v149
	v_and_b32_e32 v147, 0xffff0000, v149
	v_pk_fma_f32 v[150:151], v[166:167], v[168:169], v[150:151]
	v_pk_fma_f32 v[144:145], v[162:163], v[146:147], v[144:145]
	v_lshl_add_u64 v[156:157], v[176:177], 2, v[156:157]
	global_store_dwordx4 v[156:157], v[150:153], off
	global_store_dwordx4 v[156:157], v[142:145], off offset:16
	v_pk_mul_f32 v[166:167], v[144:145], v[144:145]
	v_cvt_pk_bf16_f32 v149, v144, v145
	v_pk_mul_f32 v[144:145], v[8:9], v[154:155] op_sel_hi:[1,0]
	v_lshlrev_b64 v[158:159], 11, v[184:185]
	v_pk_mul_f32 v[162:163], v[152:153], v[152:153]
	v_cvt_pk_bf16_f32 v147, v152, v153
	s_waitcnt vmcnt(8)
	v_lshlrev_b32_e32 v152, 16, v134
	v_and_b32_e32 v153, 0xffff0000, v134
	v_lshl_add_u64 v[158:159], s[26:27], 0, v[158:159]
	v_exp_f32_e32 v134, v144
	v_pk_mul_f32 v[164:165], v[142:143], v[142:143]
	v_cvt_pk_bf16_f32 v146, v150, v151
	v_cvt_pk_bf16_f32 v148, v142, v143
	v_lshl_add_u64 v[142:143], v[176:177], 1, v[158:159]
	v_exp_f32_e32 v145, v145
	global_store_dwordx4 v[142:143], v[146:149], off
	v_pk_mul_f32 v[160:161], v[150:151], v[150:151]
	v_add_f32_e32 v134, 1.0, v134
	v_pk_mul_f32 v[146:147], v[6:7], v[154:155] op_sel_hi:[1,0]
	v_rcp_f32_e32 v144, v134
	v_exp_f32_e32 v150, v146
	v_exp_f32_e32 v151, v147
	v_pk_mul_f32 v[146:147], v[2:3], v[154:155] op_sel_hi:[1,0]
	v_add_f32_e32 v134, 1.0, v145
	v_rcp_f32_e32 v145, v134
	v_exp_f32_e32 v146, v146
	v_exp_f32_e32 v147, v147
	v_pk_mul_f32 v[148:149], v[4:5], v[154:155] op_sel_hi:[1,0]
	v_lshlrev_b32_e32 v134, 16, v135
	v_and_b32_e32 v135, 0xffff0000, v135
	v_pk_fma_f32 v[140:141], v[144:145], v[134:135], v[140:141]
	v_add_f32_e32 v134, 1.0, v146
	v_exp_f32_e32 v146, v148
	v_add_f32_e32 v135, 1.0, v147
	v_exp_f32_e32 v147, v149
	v_add_f32_e32 v150, 1.0, v150
	v_add_f32_e32 v151, 1.0, v151
	v_lshlrev_b32_e32 v144, 16, v136
	v_and_b32_e32 v145, 0xffff0000, v136
	v_add_f32_e32 v136, 1.0, v146
	v_rcp_f32_e32 v150, v150
	v_rcp_f32_e32 v151, v151
	v_rcp_f32_e32 v134, v134
	v_rcp_f32_e32 v135, v135
	v_rcp_f32_e32 v146, v136
	v_add_f32_e32 v136, 1.0, v147
	v_rcp_f32_e32 v147, v136
	v_pk_fma_f32 v[138:139], v[150:151], v[152:153], v[138:139]
	v_pk_fma_f32 v[130:131], v[134:135], v[144:145], v[130:131]
	v_lshlrev_b32_e32 v134, 16, v137
	v_and_b32_e32 v135, 0xffff0000, v137
	v_pk_fma_f32 v[132:133], v[146:147], v[134:135], v[132:133]
	v_pk_mul_f32 v[134:135], v[138:139], v[138:139]
	v_pk_mul_f32 v[136:137], v[140:141], v[140:141]
	v_add_f32_e32 v134, v134, v135
	v_add_f32_e32 v136, v136, v137
	v_pk_mul_f32 v[144:145], v[130:131], v[130:131]
	v_pk_mul_f32 v[146:147], v[132:133], v[132:133]
	v_add_f32_e32 v134, v134, v136
	v_add_f32_e32 v135, v166, v167
	v_add_f32_e32 v136, v164, v165
	v_add_f32_e32 v146, v146, v147
	v_add_f32_e32 v144, v144, v145
	v_add_f32_e32 v135, v136, v135
	v_add_f32_e32 v136, v162, v163
	v_add_f32_e32 v137, v160, v161
	v_add_f32_e32 v144, v144, v146
	v_add_f32_e32 v136, v137, v136
	v_add_f32_e32 v134, v134, v144
	v_add_f32_e32 v135, v136, v135
	v_add_f32_e32 v144, v135, v134
	global_store_dwordx4 v[156:157], v[138:141], off offset:512
	global_store_dwordx4 v[156:157], v[130:133], off offset:528
	v_cvt_pk_bf16_f32 v134, v138, v139
	ds_swizzle_b32 v138, v144 offset:swizzle(SWAP,16)
	v_cvt_pk_bf16_f32 v136, v130, v131
	v_cvt_pk_bf16_f32 v135, v140, v141
	v_cvt_pk_bf16_f32 v137, v132, v133
	global_store_dwordx4 v[142:143], v[134:137], off offset:256
	s_waitcnt lgkmcnt(0)
	v_add_f32_e32 v130, v144, v138
	v_mov_b32_e32 v131, v130
	s_nop 1
	v_permlane32_swap_b32_e32 v130, v131
	s_and_saveexec_b64 s[6:7], vcc
	s_cbranch_execz .LBB0_1518
	v_add_f32_e32 v132, v130, v131
	v_lshlrev_b64 v[130:131], 6, v[184:185]
	v_lshl_add_u64 v[130:131], s[22:23], 0, v[130:131]
	s_lshl_b32 s22, s18, 2
	s_ashr_i32 s23, s22, 31
	v_lshl_add_u64 v[130:131], s[22:23], 2, v[130:131]
	s_lshl_b32 s68, s9, 2
	v_lshl_add_u64 v[130:131], v[130:131], 0, s[68:69]
	global_store_dword v[130:131], v132, off

.LBB0_1519:
	s_mov_b64 s[6:7], s[54:55]
	s_add_u32 s24, s6, 0x1a0d2000
	s_addc_u32 s25, s7, 0
	s_lshl_b32 s20, s20, 8
	s_lshl_b32 s11, s11, 6
	s_add_i32 s26, s11, s20
	v_or_b32_e32 v130, s26, v179
	v_mov_b32_e32 v175, v1
	v_lshl_add_u64 v[132:133], s[6:7], 0, v[174:175]
	s_mov_b64 s[6:7], 0xaa88000
	v_ashrrev_i32_e32 v131, 31, v130
	v_lshl_add_u64 v[132:133], v[132:133], 0, s[6:7]
	v_lshlrev_b64 v[134:135], 6, v[130:131]
	v_or_b32_e32 v136, 16, v130
	s_mov_b64 s[22:23], s[52:53]
	v_lshl_add_u64 v[134:135], v[132:133], 0, v[134:135]
	v_ashrrev_i32_e32 v137, 31, v136
	global_load_dwordx4 v[158:161], v[134:135], off
	v_lshlrev_b64 v[136:137], 6, v[136:137]
	v_lshl_add_u64 v[136:137], v[132:133], 0, v[136:137]
	global_load_dwordx4 v[170:173], v[136:137], off
	s_lshl_b32 s6, s18, 8
	s_lshl_b32 s7, s9, 5
	v_or_b32_e32 v131, s11, v179
	s_or_b32 s6, s7, s6
	v_add_u32_e32 v186, s20, v131
	v_lshl_or_b32 v184, v181, 3, s6
	v_ashrrev_i32_e32 v187, 31, v186
	v_ashrrev_i32_e32 v185, 31, v184
	v_lshlrev_b64 v[138:139], 10, v[186:187]
	v_lshl_add_u64 v[138:139], v[138:139], 0, v[184:185]
	v_lshlrev_b64 v[154:155], 1, v[138:139]
	v_lshl_add_u64 v[140:141], s[24:25], 0, v[154:155]
	global_load_dwordx4 v[192:195], v[140:141], off
	v_lshl_add_u64 v[156:157], v[138:139], 2, s[22:23]
	global_load_dwordx4 v[198:201], v[156:157], off offset:16
	global_load_dwordx4 v[202:205], v[156:157], off
	v_or_b32_e32 v136, 32, v130
	v_or_b32_e32 v130, 48, v130
	v_or_b32_e32 v190, 16, v186
	v_ashrrev_i32_e32 v137, 31, v136
	v_ashrrev_i32_e32 v131, 31, v130
	v_ashrrev_i32_e32 v191, 31, v190
	v_lshlrev_b64 v[136:137], 6, v[136:137]
	v_lshlrev_b64 v[130:131], 6, v[130:131]
	v_lshlrev_b64 v[140:141], 10, v[190:191]
	v_lshl_add_u64 v[136:137], v[132:133], 0, v[136:137]
	v_lshl_add_u64 v[130:131], v[132:133], 0, v[130:131]
	v_add_co_u32_e32 v132, vcc, s84, v134
	v_lshl_add_u64 v[162:163], v[140:141], 0, v[184:185]
	v_or_b32_e32 v154, 0x100, v154
	v_lshlrev_b64 v[138:139], 12, v[186:187]
	v_addc_co_u32_e32 v133, vcc, 0, v135, vcc
	v_lshl_add_u64 v[164:165], v[162:163], 2, s[22:23]
	v_lshl_add_u64 v[214:215], s[24:25], 0, v[154:155]
	v_lshl_add_u64 v[218:219], s[22:23], 0, v[138:139]
	global_load_dwordx4 v[150:153], v[136:137], off
	global_load_dwordx4 v[146:149], v[130:131], off
	global_load_dwordx4 v[142:145], v[132:133], off
	global_load_dwordx4 v[138:141], v[132:133], off offset:1024
	s_nop 0
	global_load_dwordx4 v[134:137], v[132:133], off offset:2048
	s_nop 0
	global_load_dwordx4 v[130:133], v[132:133], off offset:3072
	s_nop 0
	global_load_dwordx4 v[206:209], v[156:157], off offset:528
	global_load_dwordx4 v[210:213], v[156:157], off offset:512
	v_lshlrev_b64 v[188:189], 1, v[162:163]
	global_load_dwordx4 v[166:169], v[164:165], off offset:16
	global_load_dwordx4 v[174:177], v[164:165], off
	global_load_dwordx4 v[154:157], v[164:165], off offset:528
	s_nop 0
	global_load_dwordx4 v[162:165], v[164:165], off offset:512
	v_lshl_add_u64 v[220:221], s[24:25], 0, v[188:189]
	global_load_dwordx4 v[214:217], v[214:215], off
	v_or_b32_e32 v188, 0x100, v188
	v_lshl_add_u64 v[188:189], s[24:25], 0, v[188:189]
	s_waitcnt vmcnt(0)
	v_mov_b32_e32 v222, v159
	v_mov_b32_e32 v223, v160
	v_mov_b32_e32 v159, v161
	v_pk_add_f32 v[158:159], v[222:223], v[158:159]
	v_mov_b32_e32 v160, v171
	v_mov_b32_e32 v161, v172
	v_mov_b32_e32 v171, v173
	v_add_f32_e32 v179, v158, v159
	v_pk_add_f32 v[158:159], v[160:161], v[170:171]
	ds_swizzle_b32 v181, v179 offset:swizzle(SWAP,16)
	v_add_f32_e32 v183, v158, v159
	global_load_dwordx4 v[170:173], v[220:221], off
	global_load_dwordx4 v[158:161], v[188:189], off
	ds_swizzle_b32 v187, v183 offset:swizzle(SWAP,16)
	s_waitcnt lgkmcnt(1)
	v_add_f32_e32 v179, v179, v181
	v_mov_b32_e32 v181, v179
	s_nop 1
	v_permlane32_swap_b32_e32 v179, v181
	v_add_f32_e32 v179, v179, v181
	v_fmamk_f32 v179, v179, 0x3a800000, v254
	v_rsq_f32_e32 v220, v179
	s_nop 0
	v_mul_f32_e32 v220, 0xbfb8aa3b, v220
	s_waitcnt lgkmcnt(0)
	v_add_f32_e32 v183, v183, v187
	v_mov_b32_e32 v187, v183
	s_nop 1
	v_permlane32_swap_b32_e32 v183, v187
	v_pk_mul_f32 v[126:127], v[126:127], v[220:221] op_sel_hi:[1,0]
	v_pk_mul_f32 v[222:223], v[124:125], v[220:221] op_sel_hi:[1,0]
	v_exp_f32_e32 v124, v126
	v_exp_f32_e32 v125, v127
	v_pk_mul_f32 v[128:129], v[128:129], v[220:221] op_sel_hi:[1,0]
	v_lshlrev_b32_e32 v126, 16, v192
	v_add_f32_e32 v124, 1.0, v124
	v_add_f32_e32 v125, 1.0, v125
	v_rcp_f32_e32 v124, v124
	v_rcp_f32_e32 v125, v125
	v_exp_f32_e32 v128, v128
	v_exp_f32_e32 v129, v129
	v_and_b32_e32 v127, 0xffff0000, v192
	v_pk_fma_f32 v[124:125], v[124:125], v[126:127], v[202:203]
	v_add_f32_e32 v126, 1.0, v128
	v_add_f32_e32 v127, 1.0, v129
	v_rcp_f32_e32 v126, v126
	v_rcp_f32_e32 v127, v127
	v_add_f32_e32 v179, v183, v187
	v_pk_mul_f32 v[122:123], v[122:123], v[220:221] op_sel_hi:[1,0]
	v_lshlrev_b32_e32 v128, 16, v193
	v_and_b32_e32 v129, 0xffff0000, v193
	v_fmamk_f32 v179, v179, 0x3a800000, v254
	v_pk_fma_f32 v[126:127], v[126:127], v[128:129], v[204:205]
	v_rsq_f32_e32 v188, v179
	s_nop 0
	v_mul_f32_e32 v188, 0xbfb8aa3b, v188
	v_exp_f32_e32 v122, v122
	v_exp_f32_e32 v123, v123
	v_exp_f32_e32 v179, v222
	v_exp_f32_e32 v181, v223
	v_add_f32_e32 v122, 1.0, v122
	v_add_f32_e32 v123, 1.0, v123
	v_add_f32_e32 v179, 1.0, v179
	v_rcp_f32_e32 v122, v122
	v_rcp_f32_e32 v123, v123
	v_rcp_f32_e32 v202, v179
	v_add_f32_e32 v179, 1.0, v181
	v_rcp_f32_e32 v203, v179
	v_lshlrev_b32_e32 v128, 16, v194
	v_and_b32_e32 v129, 0xffff0000, v194
	v_pk_fma_f32 v[192:193], v[122:123], v[128:129], v[198:199]
	v_lshlrev_b32_e32 v122, 16, v195
	v_and_b32_e32 v123, 0xffff0000, v195
	v_pk_fma_f32 v[194:195], v[202:203], v[122:123], v[200:201]
	v_lshlrev_b64 v[122:123], 2, v[184:185]
	v_lshl_add_u64 v[128:129], v[218:219], 0, v[122:123]
	v_pk_mul_f32 v[118:119], v[118:119], v[220:221] op_sel_hi:[1,0]
	global_store_dwordx4 v[128:129], v[124:127], off
	global_store_dwordx4 v[128:129], v[192:195], off offset:16
	v_pk_mul_f32 v[120:121], v[120:121], v[220:221] op_sel_hi:[1,0]
	v_pk_mul_f32 v[124:125], v[116:117], v[220:221] op_sel_hi:[1,0]
	v_exp_f32_e32 v118, v118
	v_exp_f32_e32 v119, v119
	v_pk_mul_f32 v[116:117], v[114:115], v[220:221] op_sel_hi:[1,0]
	v_add_f32_e32 v114, 1.0, v118
	v_add_f32_e32 v115, 1.0, v119
	v_rcp_f32_e32 v114, v114
	v_rcp_f32_e32 v115, v115
	v_exp_f32_e32 v120, v120
	v_exp_f32_e32 v121, v121
	v_lshlrev_b32_e32 v118, 16, v214
	v_and_b32_e32 v119, 0xffff0000, v214
	v_pk_fma_f32 v[114:115], v[114:115], v[118:119], v[210:211]
	v_add_f32_e32 v118, 1.0, v120
	v_add_f32_e32 v119, 1.0, v121
	v_rcp_f32_e32 v118, v118
	v_rcp_f32_e32 v119, v119
	v_lshlrev_b32_e32 v120, 16, v215
	v_and_b32_e32 v121, 0xffff0000, v215
	v_exp_f32_e32 v126, v116
	v_exp_f32_e32 v127, v117
	v_pk_fma_f32 v[116:117], v[118:119], v[120:121], v[212:213]
	v_exp_f32_e32 v124, v124
	v_exp_f32_e32 v125, v125
	v_add_f32_e32 v118, 1.0, v126
	v_add_f32_e32 v119, 1.0, v127
	v_rcp_f32_e32 v118, v118
	v_rcp_f32_e32 v119, v119
	v_add_f32_e32 v124, 1.0, v124
	v_add_f32_e32 v125, 1.0, v125
	v_rcp_f32_e32 v124, v124
	v_rcp_f32_e32 v125, v125
	v_lshlrev_b32_e32 v120, 16, v216
	v_and_b32_e32 v121, 0xffff0000, v216
	v_pk_fma_f32 v[118:119], v[118:119], v[120:121], v[206:207]
	v_lshlrev_b32_e32 v120, 16, v217
	v_and_b32_e32 v121, 0xffff0000, v217
	v_pk_mul_f32 v[110:111], v[110:111], v[188:189] op_sel_hi:[1,0]
	v_pk_fma_f32 v[120:121], v[124:125], v[120:121], v[208:209]
	global_store_dwordx4 v[128:129], v[114:117], off offset:512
	global_store_dwordx4 v[128:129], v[118:121], off offset:528
	v_pk_mul_f32 v[112:113], v[112:113], v[188:189] op_sel_hi:[1,0]
	v_pk_mul_f32 v[116:117], v[108:109], v[188:189] op_sel_hi:[1,0]
	v_exp_f32_e32 v110, v110
	v_exp_f32_e32 v111, v111
	v_pk_mul_f32 v[108:109], v[106:107], v[188:189] op_sel_hi:[1,0]
	v_add_f32_e32 v106, 1.0, v110
	v_add_f32_e32 v107, 1.0, v111
	v_rcp_f32_e32 v106, v106
	v_rcp_f32_e32 v107, v107
	v_exp_f32_e32 v112, v112
	v_exp_f32_e32 v113, v113
	s_waitcnt vmcnt(5)
	v_lshlrev_b32_e32 v110, 16, v170
	v_and_b32_e32 v111, 0xffff0000, v170
	v_pk_fma_f32 v[106:107], v[106:107], v[110:111], v[174:175]
	v_add_f32_e32 v110, 1.0, v112
	v_add_f32_e32 v111, 1.0, v113
	v_rcp_f32_e32 v110, v110
	v_rcp_f32_e32 v111, v111
	v_lshlrev_b32_e32 v112, 16, v171
	v_and_b32_e32 v113, 0xffff0000, v171
	v_exp_f32_e32 v118, v108
	v_exp_f32_e32 v119, v109
	v_pk_fma_f32 v[108:109], v[110:111], v[112:113], v[176:177]
	v_exp_f32_e32 v116, v116
	v_exp_f32_e32 v117, v117
	v_add_f32_e32 v110, 1.0, v118
	v_add_f32_e32 v111, 1.0, v119
	v_rcp_f32_e32 v110, v110
	v_rcp_f32_e32 v111, v111
	v_add_f32_e32 v116, 1.0, v116
	v_add_f32_e32 v117, 1.0, v117
	v_rcp_f32_e32 v116, v116
	v_rcp_f32_e32 v117, v117
	v_lshlrev_b64 v[114:115], 12, v[190:191]
	v_lshl_add_u64 v[114:115], s[22:23], 0, v[114:115]
	v_lshlrev_b32_e32 v112, 16, v172
	v_and_b32_e32 v113, 0xffff0000, v172
	v_pk_fma_f32 v[110:111], v[110:111], v[112:113], v[166:167]
	v_lshlrev_b32_e32 v112, 16, v173
	v_and_b32_e32 v113, 0xffff0000, v173
	v_lshl_add_u64 v[114:115], v[114:115], 0, v[122:123]
	v_pk_mul_f32 v[102:103], v[102:103], v[188:189] op_sel_hi:[1,0]
	v_pk_fma_f32 v[112:113], v[116:117], v[112:113], v[168:169]
	global_store_dwordx4 v[114:115], v[106:109], off
	global_store_dwordx4 v[114:115], v[110:113], off offset:16
	v_pk_mul_f32 v[104:105], v[104:105], v[188:189] op_sel_hi:[1,0]
	v_pk_mul_f32 v[106:107], v[100:101], v[188:189] op_sel_hi:[1,0]
	v_exp_f32_e32 v102, v102
	v_exp_f32_e32 v103, v103
	v_pk_mul_f32 v[100:101], v[98:99], v[188:189] op_sel_hi:[1,0]
	v_add_f32_e32 v98, 1.0, v102
	v_add_f32_e32 v99, 1.0, v103
	v_rcp_f32_e32 v98, v98
	v_rcp_f32_e32 v99, v99
	v_exp_f32_e32 v104, v104
	v_exp_f32_e32 v105, v105
	s_waitcnt vmcnt(6)
	v_lshlrev_b32_e32 v102, 16, v158
	v_and_b32_e32 v103, 0xffff0000, v158
	v_pk_fma_f32 v[98:99], v[98:99], v[102:103], v[162:163]
	v_add_f32_e32 v102, 1.0, v104
	v_add_f32_e32 v103, 1.0, v105
	v_rcp_f32_e32 v102, v102
	v_rcp_f32_e32 v103, v103
	v_lshlrev_b32_e32 v104, 16, v159
	v_and_b32_e32 v105, 0xffff0000, v159
	v_exp_f32_e32 v108, v100
	v_exp_f32_e32 v109, v101
	v_pk_fma_f32 v[100:101], v[102:103], v[104:105], v[164:165]
	v_exp_f32_e32 v106, v106
	v_exp_f32_e32 v107, v107
	v_add_f32_e32 v102, 1.0, v108
	v_add_f32_e32 v103, 1.0, v109
	v_rcp_f32_e32 v102, v102
	v_rcp_f32_e32 v103, v103
	v_add_f32_e32 v106, 1.0, v106
	v_add_f32_e32 v107, 1.0, v107
	v_rcp_f32_e32 v106, v106
	v_rcp_f32_e32 v107, v107
	v_lshlrev_b32_e32 v104, 16, v160
	v_and_b32_e32 v105, 0xffff0000, v160
	v_or_b32_e32 v166, 32, v186
	v_pk_fma_f32 v[102:103], v[102:103], v[104:105], v[154:155]
	v_lshlrev_b32_e32 v104, 16, v161
	v_and_b32_e32 v105, 0xffff0000, v161
	v_ashrrev_i32_e32 v167, 31, v166
	v_pk_fma_f32 v[104:105], v[106:107], v[104:105], v[156:157]
	global_store_dwordx4 v[114:115], v[98:101], off offset:512
	global_store_dwordx4 v[114:115], v[102:105], off offset:528
	v_or_b32_e32 v170, 48, v186
	v_lshlrev_b64 v[98:99], 10, v[166:167]
	v_lshl_add_u64 v[98:99], v[98:99], 0, v[184:185]
	v_lshlrev_b64 v[100:101], 1, v[98:99]
	v_lshl_add_u64 v[102:103], s[24:25], 0, v[100:101]
	global_load_dwordx4 v[126:129], v[102:103], off
	v_lshl_add_u64 v[98:99], v[98:99], 2, s[22:23]
	global_load_dwordx4 v[154:157], v[98:99], off
	v_mov_b32_e32 v102, v151
	v_mov_b32_e32 v103, v152
	v_mov_b32_e32 v151, v153
	v_pk_add_f32 v[102:103], v[102:103], v[150:151]
	global_load_dwordx4 v[150:153], v[98:99], off offset:16
	v_add_f32_e32 v102, v102, v103
	ds_swizzle_b32 v103, v102 offset:swizzle(SWAP,16)
	v_or_b32_e32 v100, 0x100, v100
	v_ashrrev_i32_e32 v171, 31, v170
	v_lshlrev_b64 v[166:167], 12, v[166:167]
	v_lshl_add_u64 v[166:167], s[22:23], 0, v[166:167]
	s_waitcnt lgkmcnt(0)
	v_add_f32_e32 v104, v102, v103
	v_mov_b32_e32 v102, v147
	v_mov_b32_e32 v103, v148
	v_mov_b32_e32 v147, v149
	v_pk_add_f32 v[102:103], v[102:103], v[146:147]
	global_load_dwordx4 v[146:149], v[98:99], off offset:528
	global_load_dwordx4 v[158:161], v[98:99], off offset:512
	v_lshl_add_u64 v[98:99], s[24:25], 0, v[100:101]
	global_load_dwordx4 v[162:165], v[98:99], off
	v_add_f32_e32 v102, v102, v103
	ds_swizzle_b32 v103, v102 offset:swizzle(SWAP,16)
	v_mov_b32_e32 v105, v104
	s_nop 1
	v_permlane32_swap_b32_e32 v104, v105
	v_add_f32_e32 v104, v104, v105
	s_waitcnt lgkmcnt(0)
	v_add_f32_e32 v102, v102, v103
	v_mov_b32_e32 v103, v102
	s_nop 1
	v_permlane32_swap_b32_e32 v102, v103
	v_lshlrev_b64 v[98:99], 10, v[170:171]
	v_fmamk_f32 v104, v104, 0x3a800000, v254
	v_add_f32_e32 v102, v102, v103
	v_lshl_add_u64 v[98:99], v[98:99], 0, v[184:185]
	v_rsq_f32_e32 v168, v104
	s_nop 0
	v_mul_f32_e32 v168, 0xbfb8aa3b, v168
	v_fmamk_f32 v102, v102, 0x3a800000, v254
	v_lshlrev_b64 v[104:105], 1, v[98:99]
	v_rsq_f32_e32 v124, v102
	s_nop 0
	v_mul_f32_e32 v124, 0xbfb8aa3b, v124
	v_lshl_add_u64 v[102:103], v[98:99], 2, s[22:23]
	v_lshl_add_u64 v[114:115], s[24:25], 0, v[104:105]
	v_or_b32_e32 v104, 0x100, v104
	global_load_dwordx4 v[110:113], v[102:103], off offset:16
	global_load_dwordx4 v[118:121], v[102:103], off
	global_load_dwordx4 v[98:101], v[102:103], off offset:528
	global_load_dwordx4 v[106:109], v[102:103], off offset:512
	v_lshl_add_u64 v[102:103], s[24:25], 0, v[104:105]
	global_load_dwordx4 v[114:117], v[114:115], off
	s_nop 0
	global_load_dwordx4 v[102:105], v[102:103], off
	v_pk_mul_f32 v[94:95], v[94:95], v[168:169] op_sel_hi:[1,0]
	v_pk_mul_f32 v[172:173], v[92:93], v[168:169] op_sel_hi:[1,0]
	v_exp_f32_e32 v94, v94
	v_exp_f32_e32 v95, v95
	v_pk_mul_f32 v[96:97], v[96:97], v[168:169] op_sel_hi:[1,0]
	v_pk_mul_f32 v[92:93], v[90:91], v[168:169] op_sel_hi:[1,0]
	v_add_f32_e32 v90, 1.0, v94
	v_add_f32_e32 v91, 1.0, v95
	v_rcp_f32_e32 v90, v90
	v_rcp_f32_e32 v91, v91
	v_exp_f32_e32 v96, v96
	v_exp_f32_e32 v97, v97
	v_exp_f32_e32 v125, v92
	v_pk_mul_f32 v[86:87], v[86:87], v[168:169] op_sel_hi:[1,0]
	v_pk_mul_f32 v[88:89], v[88:89], v[168:169] op_sel_hi:[1,0]
	s_waitcnt vmcnt(11)
	v_lshlrev_b32_e32 v94, 16, v126
	v_and_b32_e32 v95, 0xffff0000, v126
	s_waitcnt vmcnt(10)
	v_pk_fma_f32 v[90:91], v[90:91], v[94:95], v[154:155]
	v_add_f32_e32 v94, 1.0, v96
	v_add_f32_e32 v95, 1.0, v97
	v_rcp_f32_e32 v94, v94
	v_rcp_f32_e32 v95, v95
	v_lshlrev_b32_e32 v96, 16, v127
	v_and_b32_e32 v97, 0xffff0000, v127
	v_exp_f32_e32 v126, v93
	v_pk_fma_f32 v[92:93], v[94:95], v[96:97], v[156:157]
	v_add_f32_e32 v94, 1.0, v125
	v_exp_f32_e32 v125, v172
	v_exp_f32_e32 v127, v173
	v_add_f32_e32 v95, 1.0, v126
	v_add_f32_e32 v125, 1.0, v125
	v_rcp_f32_e32 v94, v94
	v_rcp_f32_e32 v95, v95
	v_rcp_f32_e32 v126, v125
	v_add_f32_e32 v125, 1.0, v127
	v_rcp_f32_e32 v127, v125
	v_lshlrev_b32_e32 v96, 16, v128
	v_and_b32_e32 v97, 0xffff0000, v128
	s_waitcnt vmcnt(9)
	v_pk_fma_f32 v[94:95], v[94:95], v[96:97], v[150:151]
	v_lshlrev_b32_e32 v96, 16, v129
	v_and_b32_e32 v97, 0xffff0000, v129
	v_pk_fma_f32 v[96:97], v[126:127], v[96:97], v[152:153]
	v_lshl_add_u64 v[126:127], v[166:167], 0, v[122:123]
	global_store_dwordx4 v[126:127], v[90:93], off
	global_store_dwordx4 v[126:127], v[94:97], off offset:16
	v_pk_mul_f32 v[90:91], v[84:85], v[168:169] op_sel_hi:[1,0]
	v_exp_f32_e32 v86, v86
	v_exp_f32_e32 v87, v87
	v_pk_mul_f32 v[84:85], v[82:83], v[168:169] op_sel_hi:[1,0]
	v_add_f32_e32 v82, 1.0, v86
	v_add_f32_e32 v83, 1.0, v87
	v_rcp_f32_e32 v82, v82
	v_rcp_f32_e32 v83, v83
	v_exp_f32_e32 v88, v88
	v_exp_f32_e32 v89, v89
	s_waitcnt vmcnt(8)
	v_lshlrev_b32_e32 v86, 16, v162
	v_and_b32_e32 v87, 0xffff0000, v162
	v_pk_fma_f32 v[82:83], v[82:83], v[86:87], v[158:159]
	v_add_f32_e32 v86, 1.0, v88
	v_add_f32_e32 v87, 1.0, v89
	v_rcp_f32_e32 v86, v86
	v_rcp_f32_e32 v87, v87
	v_lshlrev_b32_e32 v88, 16, v163
	v_and_b32_e32 v89, 0xffff0000, v163
	v_exp_f32_e32 v92, v84
	v_exp_f32_e32 v93, v85
	v_pk_fma_f32 v[84:85], v[86:87], v[88:89], v[160:161]
	v_exp_f32_e32 v90, v90
	v_exp_f32_e32 v91, v91
	v_add_f32_e32 v86, 1.0, v92
	v_add_f32_e32 v87, 1.0, v93
	v_rcp_f32_e32 v86, v86
	v_rcp_f32_e32 v87, v87
	v_add_f32_e32 v90, 1.0, v90
	v_add_f32_e32 v91, 1.0, v91
	v_rcp_f32_e32 v90, v90
	v_rcp_f32_e32 v91, v91
	v_lshlrev_b32_e32 v88, 16, v164
	v_and_b32_e32 v89, 0xffff0000, v164
	v_pk_fma_f32 v[86:87], v[86:87], v[88:89], v[146:147]
	v_lshlrev_b32_e32 v88, 16, v165
	v_and_b32_e32 v89, 0xffff0000, v165
	v_pk_mul_f32 v[78:79], v[78:79], v[124:125] op_sel_hi:[1,0]
	v_pk_fma_f32 v[88:89], v[90:91], v[88:89], v[148:149]
	global_store_dwordx4 v[126:127], v[82:85], off offset:512
	global_store_dwordx4 v[126:127], v[86:89], off offset:528
	v_pk_mul_f32 v[80:81], v[80:81], v[124:125] op_sel_hi:[1,0]
	v_pk_mul_f32 v[84:85], v[76:77], v[124:125] op_sel_hi:[1,0]
	v_exp_f32_e32 v78, v78
	v_exp_f32_e32 v79, v79
	v_pk_mul_f32 v[76:77], v[74:75], v[124:125] op_sel_hi:[1,0]
	v_add_f32_e32 v74, 1.0, v78
	v_add_f32_e32 v75, 1.0, v79
	v_rcp_f32_e32 v74, v74
	v_rcp_f32_e32 v75, v75
	v_exp_f32_e32 v80, v80
	v_exp_f32_e32 v81, v81
	s_waitcnt vmcnt(5)
	v_lshlrev_b32_e32 v78, 16, v114
	v_and_b32_e32 v79, 0xffff0000, v114
	v_pk_fma_f32 v[74:75], v[74:75], v[78:79], v[118:119]
	v_add_f32_e32 v78, 1.0, v80
	v_add_f32_e32 v79, 1.0, v81
	v_rcp_f32_e32 v78, v78
	v_rcp_f32_e32 v79, v79
	v_lshlrev_b32_e32 v80, 16, v115
	v_and_b32_e32 v81, 0xffff0000, v115
	v_exp_f32_e32 v86, v76
	v_exp_f32_e32 v87, v77
	v_pk_fma_f32 v[76:77], v[78:79], v[80:81], v[120:121]
	v_exp_f32_e32 v84, v84
	v_exp_f32_e32 v85, v85
	v_add_f32_e32 v78, 1.0, v86
	v_add_f32_e32 v79, 1.0, v87
	v_rcp_f32_e32 v78, v78
	v_rcp_f32_e32 v79, v79
	v_add_f32_e32 v84, 1.0, v84
	v_add_f32_e32 v85, 1.0, v85
	v_rcp_f32_e32 v84, v84
	v_rcp_f32_e32 v85, v85
	v_lshlrev_b64 v[82:83], 12, v[170:171]
	v_lshl_add_u64 v[82:83], s[22:23], 0, v[82:83]
	v_lshlrev_b32_e32 v80, 16, v116
	v_and_b32_e32 v81, 0xffff0000, v116
	v_pk_fma_f32 v[78:79], v[78:79], v[80:81], v[110:111]
	v_lshlrev_b32_e32 v80, 16, v117
	v_and_b32_e32 v81, 0xffff0000, v117
	v_lshl_add_u64 v[82:83], v[82:83], 0, v[122:123]
	v_pk_mul_f32 v[70:71], v[70:71], v[124:125] op_sel_hi:[1,0]
	v_pk_fma_f32 v[80:81], v[84:85], v[80:81], v[112:113]
	global_store_dwordx4 v[82:83], v[74:77], off
	global_store_dwordx4 v[82:83], v[78:81], off offset:16
	v_pk_mul_f32 v[72:73], v[72:73], v[124:125] op_sel_hi:[1,0]
	v_pk_mul_f32 v[74:75], v[68:69], v[124:125] op_sel_hi:[1,0]
	v_exp_f32_e32 v70, v70
	v_exp_f32_e32 v71, v71
	v_pk_mul_f32 v[68:69], v[66:67], v[124:125] op_sel_hi:[1,0]
	v_add_f32_e32 v66, 1.0, v70
	v_add_f32_e32 v67, 1.0, v71
	v_rcp_f32_e32 v66, v66
	v_rcp_f32_e32 v67, v67
	v_exp_f32_e32 v72, v72
	v_exp_f32_e32 v73, v73
	s_waitcnt vmcnt(6)
	v_lshlrev_b32_e32 v70, 16, v102
	v_and_b32_e32 v71, 0xffff0000, v102
	v_pk_fma_f32 v[66:67], v[66:67], v[70:71], v[106:107]
	v_add_f32_e32 v70, 1.0, v72
	v_add_f32_e32 v71, 1.0, v73
	v_rcp_f32_e32 v70, v70
	v_rcp_f32_e32 v71, v71
	v_lshlrev_b32_e32 v72, 16, v103
	v_and_b32_e32 v73, 0xffff0000, v103
	v_exp_f32_e32 v76, v68
	v_exp_f32_e32 v77, v69
	v_pk_fma_f32 v[68:69], v[70:71], v[72:73], v[108:109]
	v_exp_f32_e32 v74, v74
	v_exp_f32_e32 v75, v75
	v_add_f32_e32 v70, 1.0, v76
	v_add_f32_e32 v71, 1.0, v77
	v_rcp_f32_e32 v70, v70
	v_rcp_f32_e32 v71, v71
	v_add_f32_e32 v74, 1.0, v74
	v_add_f32_e32 v75, 1.0, v75
	v_rcp_f32_e32 v74, v74
	v_rcp_f32_e32 v75, v75
	v_lshlrev_b32_e32 v72, 16, v104
	v_and_b32_e32 v73, 0xffff0000, v104
	v_add_u32_e32 v116, 0x80, v186
	v_pk_fma_f32 v[70:71], v[70:71], v[72:73], v[98:99]
	v_lshlrev_b32_e32 v72, 16, v105
	v_and_b32_e32 v73, 0xffff0000, v105
	v_ashrrev_i32_e32 v117, 31, v116
	v_pk_fma_f32 v[72:73], v[74:75], v[72:73], v[100:101]
	global_store_dwordx4 v[82:83], v[66:69], off offset:512
	global_store_dwordx4 v[82:83], v[70:73], off offset:528
	v_add_u32_e32 v120, 0x90, v186
	v_lshlrev_b64 v[66:67], 10, v[116:117]
	v_lshl_add_u64 v[66:67], v[66:67], 0, v[184:185]
	v_lshlrev_b64 v[68:69], 1, v[66:67]
	v_lshl_add_u64 v[70:71], s[24:25], 0, v[68:69]
	global_load_dwordx4 v[92:95], v[70:71], off
	v_lshl_add_u64 v[66:67], v[66:67], 2, s[22:23]
	global_load_dwordx4 v[96:99], v[66:67], off
	global_load_dwordx4 v[100:103], v[66:67], off offset:16
	v_or_b32_e32 v68, 0x100, v68
	global_load_dwordx4 v[104:107], v[66:67], off offset:528
	global_load_dwordx4 v[108:111], v[66:67], off offset:512
	v_lshl_add_u64 v[66:67], s[24:25], 0, v[68:69]
	global_load_dwordx4 v[112:115], v[66:67], off
	v_mov_b32_e32 v70, v143
	v_mov_b32_e32 v71, v144
	v_mov_b32_e32 v143, v145
	v_pk_add_f32 v[70:71], v[70:71], v[142:143]
	v_ashrrev_i32_e32 v121, 31, v120
	v_add_f32_e32 v70, v70, v71
	ds_swizzle_b32 v71, v70 offset:swizzle(SWAP,16)
	v_lshlrev_b64 v[66:67], 10, v[120:121]
	v_lshl_add_u64 v[66:67], v[66:67], 0, v[184:185]
	v_lshlrev_b64 v[116:117], 12, v[116:117]
	v_lshl_add_u64 v[116:117], s[22:23], 0, v[116:117]
	s_waitcnt lgkmcnt(0)
	v_add_f32_e32 v72, v70, v71
	v_mov_b32_e32 v70, v139
	v_mov_b32_e32 v71, v140
	v_mov_b32_e32 v139, v141
	v_pk_add_f32 v[70:71], v[70:71], v[138:139]
	v_mov_b32_e32 v73, v72
	v_add_f32_e32 v70, v70, v71
	ds_swizzle_b32 v71, v70 offset:swizzle(SWAP,16)
	v_permlane32_swap_b32_e32 v72, v73
	v_add_f32_e32 v72, v72, v73
	v_fmamk_f32 v72, v72, 0x3a800000, v254
	s_waitcnt lgkmcnt(0)
	v_add_f32_e32 v70, v70, v71
	v_mov_b32_e32 v71, v70
	s_nop 1
	v_permlane32_swap_b32_e32 v70, v71
	v_add_f32_e32 v70, v70, v71
	v_rsq_f32_e32 v118, v72
	s_nop 0
	v_mul_f32_e32 v118, 0xbfb8aa3b, v118
	v_fmamk_f32 v70, v70, 0x3a800000, v254
	v_lshlrev_b64 v[72:73], 1, v[66:67]
	v_rsq_f32_e32 v90, v70
	s_nop 0
	v_mul_f32_e32 v90, 0xbfb8aa3b, v90
	v_lshl_add_u64 v[70:71], v[66:67], 2, s[22:23]
	v_lshl_add_u64 v[82:83], s[24:25], 0, v[72:73]
	v_or_b32_e32 v72, 0x100, v72
	global_load_dwordx4 v[78:81], v[70:71], off offset:16
	global_load_dwordx4 v[86:89], v[70:71], off
	global_load_dwordx4 v[66:69], v[70:71], off offset:528
	global_load_dwordx4 v[74:77], v[70:71], off offset:512
	v_lshl_add_u64 v[70:71], s[24:25], 0, v[72:73]
	global_load_dwordx4 v[82:85], v[82:83], off
	s_nop 0
	global_load_dwordx4 v[70:73], v[70:71], off
	v_pk_mul_f32 v[62:63], v[62:63], v[118:119] op_sel_hi:[1,0]
	v_pk_mul_f32 v[124:125], v[60:61], v[118:119] op_sel_hi:[1,0]
	v_exp_f32_e32 v62, v62
	v_exp_f32_e32 v63, v63
	v_pk_mul_f32 v[64:65], v[64:65], v[118:119] op_sel_hi:[1,0]
	v_pk_mul_f32 v[60:61], v[58:59], v[118:119] op_sel_hi:[1,0]
	v_add_f32_e32 v58, 1.0, v62
	v_add_f32_e32 v59, 1.0, v63
	v_rcp_f32_e32 v58, v58
	v_rcp_f32_e32 v59, v59
	v_exp_f32_e32 v64, v64
	v_exp_f32_e32 v65, v65
	v_exp_f32_e32 v91, v60
	v_pk_mul_f32 v[54:55], v[54:55], v[118:119] op_sel_hi:[1,0]
	v_pk_mul_f32 v[56:57], v[56:57], v[118:119] op_sel_hi:[1,0]
	s_waitcnt vmcnt(11)
	v_lshlrev_b32_e32 v62, 16, v92
	v_and_b32_e32 v63, 0xffff0000, v92
	s_waitcnt vmcnt(10)
	v_pk_fma_f32 v[58:59], v[58:59], v[62:63], v[96:97]
	v_add_f32_e32 v62, 1.0, v64
	v_add_f32_e32 v63, 1.0, v65
	v_rcp_f32_e32 v62, v62
	v_rcp_f32_e32 v63, v63
	v_lshlrev_b32_e32 v64, 16, v93
	v_and_b32_e32 v65, 0xffff0000, v93
	v_exp_f32_e32 v92, v61
	v_pk_fma_f32 v[60:61], v[62:63], v[64:65], v[98:99]
	v_add_f32_e32 v62, 1.0, v91
	v_exp_f32_e32 v91, v124
	v_exp_f32_e32 v93, v125
	v_add_f32_e32 v63, 1.0, v92
	v_add_f32_e32 v91, 1.0, v91
	v_rcp_f32_e32 v62, v62
	v_rcp_f32_e32 v63, v63
	v_rcp_f32_e32 v92, v91
	v_add_f32_e32 v91, 1.0, v93
	v_rcp_f32_e32 v93, v91
	v_lshlrev_b32_e32 v64, 16, v94
	v_and_b32_e32 v65, 0xffff0000, v94
	s_waitcnt vmcnt(9)
	v_pk_fma_f32 v[62:63], v[62:63], v[64:65], v[100:101]
	v_lshlrev_b32_e32 v64, 16, v95
	v_and_b32_e32 v65, 0xffff0000, v95
	v_pk_fma_f32 v[64:65], v[92:93], v[64:65], v[102:103]
	v_lshl_add_u64 v[92:93], v[116:117], 0, v[122:123]
	global_store_dwordx4 v[92:93], v[58:61], off
	global_store_dwordx4 v[92:93], v[62:65], off offset:16
	v_pk_mul_f32 v[58:59], v[52:53], v[118:119] op_sel_hi:[1,0]
	v_exp_f32_e32 v54, v54
	v_exp_f32_e32 v55, v55
	v_pk_mul_f32 v[52:53], v[50:51], v[118:119] op_sel_hi:[1,0]
	v_add_f32_e32 v50, 1.0, v54
	v_add_f32_e32 v51, 1.0, v55
	v_rcp_f32_e32 v50, v50
	v_rcp_f32_e32 v51, v51
	v_exp_f32_e32 v56, v56
	v_exp_f32_e32 v57, v57
	s_waitcnt vmcnt(8)
	v_lshlrev_b32_e32 v54, 16, v112
	v_and_b32_e32 v55, 0xffff0000, v112
	v_pk_fma_f32 v[50:51], v[50:51], v[54:55], v[108:109]
	v_add_f32_e32 v54, 1.0, v56
	v_add_f32_e32 v55, 1.0, v57
	v_rcp_f32_e32 v54, v54
	v_rcp_f32_e32 v55, v55
	v_lshlrev_b32_e32 v56, 16, v113
	v_and_b32_e32 v57, 0xffff0000, v113
	v_exp_f32_e32 v60, v52
	v_exp_f32_e32 v61, v53
	v_pk_fma_f32 v[52:53], v[54:55], v[56:57], v[110:111]
	v_exp_f32_e32 v58, v58
	v_exp_f32_e32 v59, v59
	v_add_f32_e32 v54, 1.0, v60
	v_add_f32_e32 v55, 1.0, v61
	v_rcp_f32_e32 v54, v54
	v_rcp_f32_e32 v55, v55
	v_add_f32_e32 v58, 1.0, v58
	v_add_f32_e32 v59, 1.0, v59
	v_rcp_f32_e32 v58, v58
	v_rcp_f32_e32 v59, v59
	v_lshlrev_b32_e32 v56, 16, v114
	v_and_b32_e32 v57, 0xffff0000, v114
	v_pk_fma_f32 v[54:55], v[54:55], v[56:57], v[104:105]
	v_lshlrev_b32_e32 v56, 16, v115
	v_and_b32_e32 v57, 0xffff0000, v115
	v_pk_mul_f32 v[46:47], v[46:47], v[90:91] op_sel_hi:[1,0]
	v_pk_fma_f32 v[56:57], v[58:59], v[56:57], v[106:107]
	global_store_dwordx4 v[92:93], v[50:53], off offset:512
	global_store_dwordx4 v[92:93], v[54:57], off offset:528
	v_pk_mul_f32 v[48:49], v[48:49], v[90:91] op_sel_hi:[1,0]
	v_pk_mul_f32 v[52:53], v[44:45], v[90:91] op_sel_hi:[1,0]
	v_exp_f32_e32 v46, v46
	v_exp_f32_e32 v47, v47
	v_pk_mul_f32 v[44:45], v[42:43], v[90:91] op_sel_hi:[1,0]
	v_add_f32_e32 v42, 1.0, v46
	v_add_f32_e32 v43, 1.0, v47
	v_rcp_f32_e32 v42, v42
	v_rcp_f32_e32 v43, v43
	v_exp_f32_e32 v48, v48
	v_exp_f32_e32 v49, v49
	s_waitcnt vmcnt(5)
	v_lshlrev_b32_e32 v46, 16, v82
	v_and_b32_e32 v47, 0xffff0000, v82
	v_pk_fma_f32 v[42:43], v[42:43], v[46:47], v[86:87]
	v_add_f32_e32 v46, 1.0, v48
	v_add_f32_e32 v47, 1.0, v49
	v_rcp_f32_e32 v46, v46
	v_rcp_f32_e32 v47, v47
	v_lshlrev_b32_e32 v48, 16, v83
	v_and_b32_e32 v49, 0xffff0000, v83
	v_exp_f32_e32 v54, v44
	v_exp_f32_e32 v55, v45
	v_pk_fma_f32 v[44:45], v[46:47], v[48:49], v[88:89]
	v_exp_f32_e32 v52, v52
	v_exp_f32_e32 v53, v53
	v_add_f32_e32 v46, 1.0, v54
	v_add_f32_e32 v47, 1.0, v55
	v_rcp_f32_e32 v46, v46
	v_rcp_f32_e32 v47, v47
	v_add_f32_e32 v52, 1.0, v52
	v_add_f32_e32 v53, 1.0, v53
	v_rcp_f32_e32 v52, v52
	v_rcp_f32_e32 v53, v53
	v_lshlrev_b64 v[50:51], 12, v[120:121]
	v_lshl_add_u64 v[50:51], s[22:23], 0, v[50:51]
	v_lshlrev_b32_e32 v48, 16, v84
	v_and_b32_e32 v49, 0xffff0000, v84
	v_pk_fma_f32 v[46:47], v[46:47], v[48:49], v[78:79]
	v_lshlrev_b32_e32 v48, 16, v85
	v_and_b32_e32 v49, 0xffff0000, v85
	v_lshl_add_u64 v[50:51], v[50:51], 0, v[122:123]
	v_pk_mul_f32 v[38:39], v[38:39], v[90:91] op_sel_hi:[1,0]
	v_pk_fma_f32 v[48:49], v[52:53], v[48:49], v[80:81]
	global_store_dwordx4 v[50:51], v[42:45], off
	global_store_dwordx4 v[50:51], v[46:49], off offset:16
	v_pk_mul_f32 v[40:41], v[40:41], v[90:91] op_sel_hi:[1,0]
	v_pk_mul_f32 v[42:43], v[36:37], v[90:91] op_sel_hi:[1,0]
	v_exp_f32_e32 v38, v38
	v_exp_f32_e32 v39, v39
	v_pk_mul_f32 v[36:37], v[34:35], v[90:91] op_sel_hi:[1,0]
	v_add_f32_e32 v34, 1.0, v38
	v_add_f32_e32 v35, 1.0, v39
	v_rcp_f32_e32 v34, v34
	v_rcp_f32_e32 v35, v35
	v_exp_f32_e32 v40, v40
	v_exp_f32_e32 v41, v41
	s_waitcnt vmcnt(6)
	v_lshlrev_b32_e32 v38, 16, v70
	v_and_b32_e32 v39, 0xffff0000, v70
	v_pk_fma_f32 v[34:35], v[34:35], v[38:39], v[74:75]
	v_add_f32_e32 v38, 1.0, v40
	v_add_f32_e32 v39, 1.0, v41
	v_rcp_f32_e32 v38, v38
	v_rcp_f32_e32 v39, v39
	v_lshlrev_b32_e32 v40, 16, v71
	v_and_b32_e32 v41, 0xffff0000, v71
	v_exp_f32_e32 v44, v36
	v_exp_f32_e32 v45, v37
	v_pk_fma_f32 v[36:37], v[38:39], v[40:41], v[76:77]
	v_exp_f32_e32 v42, v42
	v_exp_f32_e32 v43, v43
	v_add_f32_e32 v38, 1.0, v44
	v_add_f32_e32 v39, 1.0, v45
	v_rcp_f32_e32 v38, v38
	v_rcp_f32_e32 v39, v39
	v_add_f32_e32 v42, 1.0, v42
	v_add_f32_e32 v43, 1.0, v43
	v_rcp_f32_e32 v42, v42
	v_rcp_f32_e32 v43, v43
	v_lshlrev_b32_e32 v40, 16, v72
	v_and_b32_e32 v41, 0xffff0000, v72
	v_add_u32_e32 v84, 0xa0, v186
	v_pk_fma_f32 v[38:39], v[38:39], v[40:41], v[66:67]
	v_lshlrev_b32_e32 v40, 16, v73
	v_and_b32_e32 v41, 0xffff0000, v73
	v_ashrrev_i32_e32 v85, 31, v84
	v_pk_fma_f32 v[40:41], v[42:43], v[40:41], v[68:69]
	global_store_dwordx4 v[50:51], v[34:37], off offset:512
	global_store_dwordx4 v[50:51], v[38:41], off offset:528
	v_add_u32_e32 v88, 0xb0, v186
	v_lshlrev_b64 v[34:35], 10, v[84:85]
	v_lshl_add_u64 v[34:35], v[34:35], 0, v[184:185]
	v_lshlrev_b64 v[36:37], 1, v[34:35]
	v_lshl_add_u64 v[38:39], s[24:25], 0, v[36:37]
	global_load_dwordx4 v[60:63], v[38:39], off
	v_lshl_add_u64 v[34:35], v[34:35], 2, s[22:23]
	global_load_dwordx4 v[64:67], v[34:35], off
	global_load_dwordx4 v[68:71], v[34:35], off offset:16
	v_or_b32_e32 v36, 0x100, v36
	global_load_dwordx4 v[72:75], v[34:35], off offset:528
	global_load_dwordx4 v[76:79], v[34:35], off offset:512
	v_lshl_add_u64 v[34:35], s[24:25], 0, v[36:37]
	global_load_dwordx4 v[80:83], v[34:35], off
	v_mov_b32_e32 v38, v135
	v_mov_b32_e32 v39, v136
	v_mov_b32_e32 v135, v137
	v_pk_add_f32 v[38:39], v[38:39], v[134:135]
	v_ashrrev_i32_e32 v89, 31, v88
	v_add_f32_e32 v38, v38, v39
	ds_swizzle_b32 v39, v38 offset:swizzle(SWAP,16)
	v_lshlrev_b64 v[34:35], 10, v[88:89]
	v_lshl_add_u64 v[34:35], v[34:35], 0, v[184:185]
	v_lshlrev_b64 v[84:85], 12, v[84:85]
	v_lshl_add_u64 v[84:85], s[22:23], 0, v[84:85]
	s_waitcnt lgkmcnt(0)
	v_add_f32_e32 v40, v38, v39
	v_mov_b32_e32 v38, v131
	v_mov_b32_e32 v39, v132
	v_mov_b32_e32 v131, v133
	v_pk_add_f32 v[38:39], v[38:39], v[130:131]
	v_mov_b32_e32 v41, v40
	v_add_f32_e32 v38, v38, v39
	ds_swizzle_b32 v39, v38 offset:swizzle(SWAP,16)
	v_permlane32_swap_b32_e32 v40, v41
	v_add_f32_e32 v40, v40, v41
	v_fmamk_f32 v40, v40, 0x3a800000, v254
	s_waitcnt lgkmcnt(0)
	v_add_f32_e32 v38, v38, v39
	v_mov_b32_e32 v39, v38
	s_nop 1
	v_permlane32_swap_b32_e32 v38, v39
	v_add_f32_e32 v38, v38, v39
	v_rsq_f32_e32 v86, v40
	s_nop 0
	v_mul_f32_e32 v86, 0xbfb8aa3b, v86
	v_fmamk_f32 v38, v38, 0x3a800000, v254
	v_lshlrev_b64 v[40:41], 1, v[34:35]
	v_rsq_f32_e32 v58, v38
	s_nop 0
	v_mul_f32_e32 v58, 0xbfb8aa3b, v58
	v_lshl_add_u64 v[38:39], v[34:35], 2, s[22:23]
	v_lshl_add_u64 v[50:51], s[24:25], 0, v[40:41]
	v_or_b32_e32 v40, 0x100, v40
	global_load_dwordx4 v[46:49], v[38:39], off offset:16
	global_load_dwordx4 v[54:57], v[38:39], off
	global_load_dwordx4 v[34:37], v[38:39], off offset:528
	global_load_dwordx4 v[42:45], v[38:39], off offset:512
	v_lshl_add_u64 v[38:39], s[24:25], 0, v[40:41]
	global_load_dwordx4 v[50:53], v[50:51], off
	s_nop 0
	global_load_dwordx4 v[38:41], v[38:39], off
	v_pk_mul_f32 v[30:31], v[30:31], v[86:87] op_sel_hi:[1,0]
	v_pk_mul_f32 v[90:91], v[28:29], v[86:87] op_sel_hi:[1,0]
	v_exp_f32_e32 v30, v30
	v_exp_f32_e32 v31, v31
	v_pk_mul_f32 v[32:33], v[32:33], v[86:87] op_sel_hi:[1,0]
	v_pk_mul_f32 v[28:29], v[26:27], v[86:87] op_sel_hi:[1,0]
	v_add_f32_e32 v26, 1.0, v30
	v_add_f32_e32 v27, 1.0, v31
	v_rcp_f32_e32 v26, v26
	v_rcp_f32_e32 v27, v27
	v_exp_f32_e32 v32, v32
	v_exp_f32_e32 v33, v33
	v_exp_f32_e32 v59, v28
	v_pk_mul_f32 v[22:23], v[22:23], v[86:87] op_sel_hi:[1,0]
	v_pk_mul_f32 v[24:25], v[24:25], v[86:87] op_sel_hi:[1,0]
	s_waitcnt vmcnt(11)
	v_lshlrev_b32_e32 v30, 16, v60
	v_and_b32_e32 v31, 0xffff0000, v60
	s_waitcnt vmcnt(10)
	v_pk_fma_f32 v[26:27], v[26:27], v[30:31], v[64:65]
	v_add_f32_e32 v30, 1.0, v32
	v_add_f32_e32 v31, 1.0, v33
	v_rcp_f32_e32 v30, v30
	v_rcp_f32_e32 v31, v31
	v_lshlrev_b32_e32 v32, 16, v61
	v_and_b32_e32 v33, 0xffff0000, v61
	v_exp_f32_e32 v60, v29
	v_pk_fma_f32 v[28:29], v[30:31], v[32:33], v[66:67]
	v_add_f32_e32 v30, 1.0, v59
	v_exp_f32_e32 v59, v90
	v_exp_f32_e32 v61, v91
	v_add_f32_e32 v31, 1.0, v60
	v_add_f32_e32 v59, 1.0, v59
	v_rcp_f32_e32 v30, v30
	v_rcp_f32_e32 v31, v31
	v_rcp_f32_e32 v60, v59
	v_add_f32_e32 v59, 1.0, v61
	v_rcp_f32_e32 v61, v59
	v_lshlrev_b32_e32 v32, 16, v62
	v_and_b32_e32 v33, 0xffff0000, v62
	s_waitcnt vmcnt(9)
	v_pk_fma_f32 v[30:31], v[30:31], v[32:33], v[68:69]
	v_lshlrev_b32_e32 v32, 16, v63
	v_and_b32_e32 v33, 0xffff0000, v63
	v_pk_fma_f32 v[32:33], v[60:61], v[32:33], v[70:71]
	v_lshl_add_u64 v[60:61], v[84:85], 0, v[122:123]
	global_store_dwordx4 v[60:61], v[26:29], off
	global_store_dwordx4 v[60:61], v[30:33], off offset:16
	v_pk_mul_f32 v[26:27], v[20:21], v[86:87] op_sel_hi:[1,0]
	v_exp_f32_e32 v22, v22
	v_exp_f32_e32 v23, v23
	v_pk_mul_f32 v[20:21], v[18:19], v[86:87] op_sel_hi:[1,0]
	v_add_f32_e32 v18, 1.0, v22
	v_add_f32_e32 v19, 1.0, v23
	v_rcp_f32_e32 v18, v18
	v_rcp_f32_e32 v19, v19
	v_exp_f32_e32 v24, v24
	v_exp_f32_e32 v25, v25
	s_waitcnt vmcnt(8)
	v_lshlrev_b32_e32 v22, 16, v80
	v_and_b32_e32 v23, 0xffff0000, v80
	v_pk_fma_f32 v[18:19], v[18:19], v[22:23], v[76:77]
	v_add_f32_e32 v22, 1.0, v24
	v_add_f32_e32 v23, 1.0, v25
	v_rcp_f32_e32 v22, v22
	v_rcp_f32_e32 v23, v23
	v_lshlrev_b32_e32 v24, 16, v81
	v_and_b32_e32 v25, 0xffff0000, v81
	v_exp_f32_e32 v28, v20
	v_exp_f32_e32 v29, v21
	v_pk_fma_f32 v[20:21], v[22:23], v[24:25], v[78:79]
	v_exp_f32_e32 v26, v26
	v_exp_f32_e32 v27, v27
	v_add_f32_e32 v22, 1.0, v28
	v_add_f32_e32 v23, 1.0, v29
	v_rcp_f32_e32 v22, v22
	v_rcp_f32_e32 v23, v23
	v_add_f32_e32 v26, 1.0, v26
	v_add_f32_e32 v27, 1.0, v27
	v_rcp_f32_e32 v26, v26
	v_rcp_f32_e32 v27, v27
	v_lshlrev_b32_e32 v24, 16, v82
	v_and_b32_e32 v25, 0xffff0000, v82
	v_pk_fma_f32 v[22:23], v[22:23], v[24:25], v[72:73]
	v_lshlrev_b32_e32 v24, 16, v83
	v_and_b32_e32 v25, 0xffff0000, v83
	v_pk_mul_f32 v[14:15], v[14:15], v[58:59] op_sel_hi:[1,0]
	v_pk_fma_f32 v[24:25], v[26:27], v[24:25], v[74:75]
	global_store_dwordx4 v[60:61], v[18:21], off offset:512
	global_store_dwordx4 v[60:61], v[22:25], off offset:528
	v_pk_mul_f32 v[16:17], v[16:17], v[58:59] op_sel_hi:[1,0]
	v_pk_mul_f32 v[20:21], v[12:13], v[58:59] op_sel_hi:[1,0]
	v_exp_f32_e32 v14, v14
	v_exp_f32_e32 v15, v15
	v_pk_mul_f32 v[12:13], v[10:11], v[58:59] op_sel_hi:[1,0]
	v_add_f32_e32 v10, 1.0, v14
	v_add_f32_e32 v11, 1.0, v15
	v_rcp_f32_e32 v10, v10
	v_rcp_f32_e32 v11, v11
	v_exp_f32_e32 v16, v16
	v_exp_f32_e32 v17, v17
	s_waitcnt vmcnt(5)
	v_lshlrev_b32_e32 v14, 16, v50
	v_and_b32_e32 v15, 0xffff0000, v50
	v_pk_fma_f32 v[10:11], v[10:11], v[14:15], v[54:55]
	v_add_f32_e32 v14, 1.0, v16
	v_add_f32_e32 v15, 1.0, v17
	v_rcp_f32_e32 v14, v14
	v_rcp_f32_e32 v15, v15
	v_lshlrev_b32_e32 v16, 16, v51
	v_and_b32_e32 v17, 0xffff0000, v51
	v_exp_f32_e32 v22, v12
	v_exp_f32_e32 v23, v13
	v_pk_fma_f32 v[12:13], v[14:15], v[16:17], v[56:57]
	v_exp_f32_e32 v20, v20
	v_exp_f32_e32 v21, v21
	v_add_f32_e32 v14, 1.0, v22
	v_add_f32_e32 v15, 1.0, v23
	v_rcp_f32_e32 v14, v14
	v_rcp_f32_e32 v15, v15
	v_add_f32_e32 v20, 1.0, v20
	v_add_f32_e32 v21, 1.0, v21
	v_rcp_f32_e32 v20, v20
	v_rcp_f32_e32 v21, v21
	v_lshlrev_b64 v[18:19], 12, v[88:89]
	v_lshl_add_u64 v[18:19], s[22:23], 0, v[18:19]
	v_lshlrev_b32_e32 v16, 16, v52
	v_and_b32_e32 v17, 0xffff0000, v52
	v_pk_fma_f32 v[14:15], v[14:15], v[16:17], v[46:47]
	v_lshlrev_b32_e32 v16, 16, v53
	v_and_b32_e32 v17, 0xffff0000, v53
	v_lshl_add_u64 v[18:19], v[18:19], 0, v[122:123]
	v_pk_mul_f32 v[6:7], v[6:7], v[58:59] op_sel_hi:[1,0]
	v_pk_fma_f32 v[16:17], v[20:21], v[16:17], v[48:49]
	global_store_dwordx4 v[18:19], v[10:13], off
	global_store_dwordx4 v[18:19], v[14:17], off offset:16
	v_pk_mul_f32 v[8:9], v[8:9], v[58:59] op_sel_hi:[1,0]
	v_pk_mul_f32 v[10:11], v[4:5], v[58:59] op_sel_hi:[1,0]
	v_exp_f32_e32 v6, v6
	v_exp_f32_e32 v7, v7
	v_pk_mul_f32 v[4:5], v[2:3], v[58:59] op_sel_hi:[1,0]
	v_add_f32_e32 v2, 1.0, v6
	v_add_f32_e32 v3, 1.0, v7
	v_rcp_f32_e32 v2, v2
	v_rcp_f32_e32 v3, v3
	v_exp_f32_e32 v8, v8
	v_exp_f32_e32 v9, v9
	s_waitcnt vmcnt(6)
	v_lshlrev_b32_e32 v6, 16, v38
	v_and_b32_e32 v7, 0xffff0000, v38
	v_pk_fma_f32 v[2:3], v[2:3], v[6:7], v[42:43]
	v_add_f32_e32 v6, 1.0, v8
	v_add_f32_e32 v7, 1.0, v9
	v_rcp_f32_e32 v6, v6
	v_rcp_f32_e32 v7, v7
	v_lshlrev_b32_e32 v8, 16, v39
	v_and_b32_e32 v9, 0xffff0000, v39
	v_exp_f32_e32 v12, v4
	v_exp_f32_e32 v13, v5
	v_pk_fma_f32 v[4:5], v[6:7], v[8:9], v[44:45]
	v_exp_f32_e32 v10, v10
	v_exp_f32_e32 v11, v11
	v_add_f32_e32 v6, 1.0, v12
	v_add_f32_e32 v7, 1.0, v13
	v_rcp_f32_e32 v6, v6
	v_rcp_f32_e32 v7, v7
	v_add_f32_e32 v10, 1.0, v10
	v_add_f32_e32 v11, 1.0, v11
	v_rcp_f32_e32 v10, v10
	v_rcp_f32_e32 v11, v11
	v_lshlrev_b32_e32 v8, 16, v40
	v_and_b32_e32 v9, 0xffff0000, v40
	v_pk_fma_f32 v[6:7], v[6:7], v[8:9], v[34:35]
	v_lshlrev_b32_e32 v8, 16, v41
	v_and_b32_e32 v9, 0xffff0000, v41
	v_pk_fma_f32 v[8:9], v[10:11], v[8:9], v[36:37]
	global_store_dwordx4 v[18:19], v[2:5], off offset:512
	global_store_dwordx4 v[18:19], v[6:9], off offset:528
	s_andn2_b64 vcc, exec, s[16:17]
	s_mov_b64 s[6:7], -1
	s_cbranch_vccnz .LBB0_1492
